# static s_setprio 1 for the second-arriving wave group in the K loops of all four GEMM phases (raised after the extra start barrier, cleared at the epilogue; tail flips removed)
# speedup vs baseline: 1.0070x; 1.0052x over previous
.LBB0_168:
	s_ashr_i32 s0, s3, 31
	s_lshr_b32 s0, s0, 29
	s_add_i32 s0, s3, s0
	s_ashr_i32 s1, s0, 3
	s_and_b32 s0, s0, -8
	s_sub_i32 s0, s3, s0
	s_cmp_lt_i32 s0, 0
	s_movk_i32 s4, 0x61
	s_cselect_b32 s4, s4, 0x60
	s_mul_i32 s0, s4, s0
	s_add_i32 s0, s0, s1
	s_mul_hi_i32 s1, s0, 0x2aaaaaab
	s_lshr_b32 s4, s1, 31
	s_ashr_i32 s1, s1, 4
	s_add_i32 s1, s1, s4
	s_mul_i32 s4, s1, 0x60
	s_sub_i32 s14, s0, s4
	s_bfe_i32 s0, s14, 0x80000
	s_bfe_u32 s0, s0, 0x3000c
	s_add_i32 s0, s14, s0
	s_bfe_i32 s4, s0, 0x80000
	s_and_b32 s0, s0, 0xf8
	s_sub_i32 s0, s14, s0
	s_sext_i32_i16 s4, s4
	s_sext_i32_i8 s0, s0
	s_lshr_b32 s15, s4, 3
	s_lshl_b32 s1, s1, 11
	s_lshl_b32 s0, s0, 8
	s_add_i32 s8, s0, s1
	s_lshl_b32 s0, s15, 8
	s_ashr_i32 s1, s0, 31
	s_lshl_b64 s[10:11], s[0:1], 11
	s_add_u32 s4, s90, s10
	s_addc_u32 s5, s91, s11
	s_ashr_i32 s9, s8, 31
	s_lshl_b64 s[12:13], s[8:9], 11
	v_lshl_add_u64 v[4:5], s[4:5], 0, v[132:133]
	v_lshl_add_u64 v[2:3], s[4:5], 0, v[130:131]
	s_add_u32 s4, s94, s12
	s_addc_u32 s5, s95, s13
	v_lshl_add_u64 v[8:9], s[4:5], 0, v[132:133]
	v_lshl_add_u64 v[6:7], s[4:5], 0, v[130:131]
	s_or_b32 s4, s0, 0x80
	s_ashr_i32 s5, s4, 31
	s_lshl_b64 s[4:5], s[4:5], 11
	v_readfirstlane_b32 s1, v159
	s_add_u32 s4, s90, s4
	s_mov_b32 m0, s1
	v_readfirstlane_b32 s1, v160
	s_addc_u32 s5, s91, s5
	global_load_lds_dwordx4 v[4:5], off
	s_mov_b32 m0, s1
	v_readfirstlane_b32 s1, v161
	v_lshl_add_u64 v[12:13], s[4:5], 0, v[132:133]
	v_lshl_add_u64 v[10:11], s[4:5], 0, v[130:131]
	s_or_b32 s4, s8, 0x80
	global_load_lds_dwordx4 v[2:3], off
	s_mov_b32 m0, s1
	v_readfirstlane_b32 s1, v162
	s_ashr_i32 s5, s4, 31
	global_load_lds_dwordx4 v[8:9], off
	s_mov_b32 m0, s1
	v_readfirstlane_b32 s1, v163
	s_lshl_b64 s[4:5], s[4:5], 11
	global_load_lds_dwordx4 v[6:7], off
	s_mov_b32 m0, s1
	v_readfirstlane_b32 s1, v164
	s_add_u32 s4, s94, s4
	global_load_lds_dwordx4 v[12:13], off
	s_mov_b32 m0, s1
	s_addc_u32 s5, s95, s5
	v_readfirstlane_b32 s1, v165
	global_load_lds_dwordx4 v[10:11], off
	v_lshl_add_u64 v[140:141], s[4:5], 0, v[132:133]
	s_mov_b32 m0, s1
	v_readfirstlane_b32 s1, v166
	global_load_lds_dwordx4 v[140:141], off
	v_lshl_add_u64 v[142:143], s[4:5], 0, v[130:131]
	s_mov_b32 m0, s1
	s_nop 0
	global_load_lds_dwordx4 v[142:143], off
	s_and_saveexec_b64 s[4:5], s[72:73]
	s_cbranch_execz .LBB0_170
	s_barrier
	s_setprio 1

.LBB0_171:
	ds_read_b128 v[176:179], v167
	ds_read_b128 v[180:183], v167 offset:1024
	ds_read_b128 v[184:187], v167 offset:2048
	ds_read_b128 v[188:191], v167 offset:3072
	v_add_u32_e32 v157, 0xc000, v161
	v_lshl_add_u64 v[196:197], s[10:11], 0, v[148:149]
	v_readfirstlane_b32 s4, v157
	v_add_u32_e32 v175, 0xe000, v161
	v_lshl_add_u64 v[228:229], v[196:197], 0, s[36:37]
	s_mov_b32 m0, s4
	v_lshl_add_u64 v[244:245], s[10:11], 0, v[150:151]
	v_readfirstlane_b32 s4, v175
	ds_read_b128 v[192:195], v168
	ds_read_b128 v[200:203], v168 offset:1024
	ds_read_b128 v[204:207], v169
	ds_read_b128 v[208:211], v169 offset:1024
	ds_read_b128 v[212:215], v170
	ds_read_b128 v[216:219], v170 offset:1024
	ds_read_b128 v[220:223], v171
	ds_read_b128 v[224:227], v171 offset:1024
	global_load_lds_dwordx4 v[228:229], off
	v_lshl_add_u64 v[228:229], v[244:245], 0, s[36:37]
	s_mov_b32 m0, s4
	s_nop 0
	global_load_lds_dwordx4 v[228:229], off
	s_waitcnt lgkmcnt(8)
	s_barrier
	s_waitcnt lgkmcnt(0)
	s_waitcnt lgkmcnt(0)
	v_mfma_f32_16x16x32_bf16 v[126:129], v[176:179], v[192:195], v[126:129]
	v_mfma_f32_16x16x32_bf16 v[122:125], v[184:187], v[192:195], v[122:125]
	v_mfma_f32_16x16x32_bf16 v[118:121], v[176:179], v[204:207], v[118:121]
	v_mfma_f32_16x16x32_bf16 v[114:117], v[184:187], v[204:207], v[114:117]
	v_mfma_f32_16x16x32_bf16 v[110:113], v[176:179], v[212:215], v[110:113]
	v_mfma_f32_16x16x32_bf16 v[106:109], v[184:187], v[212:215], v[106:109]
	v_mfma_f32_16x16x32_bf16 v[102:105], v[176:179], v[220:223], v[102:105]
	v_mfma_f32_16x16x32_bf16 v[98:101], v[184:187], v[220:223], v[98:101]
	v_mfma_f32_16x16x32_bf16 v[126:129], v[180:183], v[200:203], v[126:129]
	v_mfma_f32_16x16x32_bf16 v[122:125], v[188:191], v[200:203], v[122:125]
	v_mfma_f32_16x16x32_bf16 v[118:121], v[180:183], v[208:211], v[118:121]
	v_mfma_f32_16x16x32_bf16 v[114:117], v[188:191], v[208:211], v[114:117]
	v_mfma_f32_16x16x32_bf16 v[110:113], v[180:183], v[216:219], v[110:113]
	v_mfma_f32_16x16x32_bf16 v[106:109], v[188:191], v[216:219], v[106:109]
	v_mfma_f32_16x16x32_bf16 v[102:105], v[180:183], v[224:227], v[102:105]
	v_mfma_f32_16x16x32_bf16 v[98:101], v[188:191], v[224:227], v[98:101]
	s_barrier
	v_lshl_add_u64 v[246:247], s[10:11], 0, v[144:145]
	v_readfirstlane_b32 s4, v159
	v_lshl_add_u64 v[248:249], v[246:247], 0, s[38:39]
	s_mov_b32 m0, s4
	ds_read_b128 v[228:231], v172
	ds_read_b128 v[232:235], v172 offset:1024
	ds_read_b128 v[236:239], v172 offset:2048
	ds_read_b128 v[240:243], v172 offset:3072
	global_load_lds_dwordx4 v[248:249], off
	v_lshl_add_u64 v[248:249], s[10:11], 0, v[146:147]
	v_readfirstlane_b32 s4, v160
	v_lshl_add_u64 v[250:251], v[248:249], 0, s[38:39]
	s_mov_b32 m0, s4
	s_nop 0
	global_load_lds_dwordx4 v[250:251], off
	s_barrier
	s_waitcnt lgkmcnt(0)
	s_waitcnt lgkmcnt(0)
	v_mfma_f32_16x16x32_bf16 v[94:97], v[228:231], v[192:195], v[94:97]
	v_mfma_f32_16x16x32_bf16 v[90:93], v[236:239], v[192:195], v[90:93]
	v_mfma_f32_16x16x32_bf16 v[86:89], v[228:231], v[204:207], v[86:89]
	v_mfma_f32_16x16x32_bf16 v[82:85], v[236:239], v[204:207], v[82:85]
	v_mfma_f32_16x16x32_bf16 v[78:81], v[228:231], v[212:215], v[78:81]
	v_mfma_f32_16x16x32_bf16 v[74:77], v[236:239], v[212:215], v[74:77]
	v_mfma_f32_16x16x32_bf16 v[70:73], v[228:231], v[220:223], v[70:73]
	v_mfma_f32_16x16x32_bf16 v[66:69], v[236:239], v[220:223], v[66:69]
	v_mfma_f32_16x16x32_bf16 v[94:97], v[232:235], v[200:203], v[94:97]
	v_mfma_f32_16x16x32_bf16 v[90:93], v[240:243], v[200:203], v[90:93]
	v_mfma_f32_16x16x32_bf16 v[86:89], v[232:235], v[208:211], v[86:89]
	v_mfma_f32_16x16x32_bf16 v[82:85], v[240:243], v[208:211], v[82:85]
	v_mfma_f32_16x16x32_bf16 v[78:81], v[232:235], v[216:219], v[78:81]
	v_mfma_f32_16x16x32_bf16 v[74:77], v[240:243], v[216:219], v[74:77]
	v_mfma_f32_16x16x32_bf16 v[70:73], v[232:235], v[224:227], v[70:73]
	v_mfma_f32_16x16x32_bf16 v[66:69], v[240:243], v[224:227], v[66:69]
	v_readfirstlane_b32 s4, v161
	v_lshl_add_u64 v[250:251], v[196:197], 0, s[58:59]
	s_mov_b32 m0, s4
	v_readfirstlane_b32 s4, v162
	s_barrier
	ds_read_b128 v[192:195], v168 offset:16384
	ds_read_b128 v[200:203], v168 offset:17408
	ds_read_b128 v[204:207], v169 offset:16384
	ds_read_b128 v[208:211], v169 offset:17408
	ds_read_b128 v[212:215], v170 offset:16384
	ds_read_b128 v[216:219], v170 offset:17408
	ds_read_b128 v[220:223], v171 offset:16384
	ds_read_b128 v[224:227], v171 offset:17408
	global_load_lds_dwordx4 v[250:251], off
	v_lshl_add_u64 v[250:251], v[244:245], 0, s[58:59]
	s_mov_b32 m0, s4
	s_nop 0
	global_load_lds_dwordx4 v[250:251], off
	s_barrier
	s_waitcnt lgkmcnt(0)
	s_waitcnt lgkmcnt(0)
	v_mfma_f32_16x16x32_bf16 v[62:65], v[176:179], v[192:195], v[62:65]
	v_mfma_f32_16x16x32_bf16 v[58:61], v[184:187], v[192:195], v[58:61]
	v_mfma_f32_16x16x32_bf16 v[54:57], v[176:179], v[204:207], v[54:57]
	v_mfma_f32_16x16x32_bf16 v[50:53], v[184:187], v[204:207], v[50:53]
	v_mfma_f32_16x16x32_bf16 v[46:49], v[176:179], v[212:215], v[46:49]
	v_mfma_f32_16x16x32_bf16 v[42:45], v[184:187], v[212:215], v[42:45]
	v_mfma_f32_16x16x32_bf16 v[38:41], v[176:179], v[220:223], v[38:41]
	v_mfma_f32_16x16x32_bf16 v[34:37], v[184:187], v[220:223], v[34:37]
	v_mfma_f32_16x16x32_bf16 v[62:65], v[180:183], v[200:203], v[62:65]
	v_mfma_f32_16x16x32_bf16 v[58:61], v[188:191], v[200:203], v[58:61]
	v_mfma_f32_16x16x32_bf16 v[54:57], v[180:183], v[208:211], v[54:57]
	v_mfma_f32_16x16x32_bf16 v[50:53], v[188:191], v[208:211], v[50:53]
	v_mfma_f32_16x16x32_bf16 v[46:49], v[180:183], v[216:219], v[46:49]
	v_mfma_f32_16x16x32_bf16 v[42:45], v[188:191], v[216:219], v[42:45]
	v_mfma_f32_16x16x32_bf16 v[38:41], v[180:183], v[224:227], v[38:41]
	v_mfma_f32_16x16x32_bf16 v[34:37], v[188:191], v[224:227], v[34:37]
	s_barrier
	v_readfirstlane_b32 s4, v163
	v_lshl_add_u64 v[176:177], v[246:247], 0, s[60:61]
	s_mov_b32 m0, s4
	v_readfirstlane_b32 s4, v164
	global_load_lds_dwordx4 v[176:177], off
	v_lshl_add_u64 v[176:177], v[248:249], 0, s[60:61]
	s_mov_b32 m0, s4
	s_nop 0
	global_load_lds_dwordx4 v[176:177], off
	s_waitcnt vmcnt(6)
	s_barrier
	v_mfma_f32_16x16x32_bf16 v[30:33], v[228:231], v[192:195], v[30:33]
	v_mfma_f32_16x16x32_bf16 v[26:29], v[236:239], v[192:195], v[26:29]
	v_mfma_f32_16x16x32_bf16 v[22:25], v[228:231], v[204:207], v[22:25]
	v_mfma_f32_16x16x32_bf16 v[18:21], v[236:239], v[204:207], v[18:21]
	v_mfma_f32_16x16x32_bf16 v[14:17], v[228:231], v[212:215], v[14:17]
	v_mfma_f32_16x16x32_bf16 v[10:13], v[236:239], v[212:215], v[10:13]
	v_mfma_f32_16x16x32_bf16 v[6:9], v[228:231], v[220:223], v[6:9]
	v_mfma_f32_16x16x32_bf16 v[2:5], v[236:239], v[220:223], v[2:5]
	v_mfma_f32_16x16x32_bf16 v[30:33], v[232:235], v[200:203], v[30:33]
	v_mfma_f32_16x16x32_bf16 v[26:29], v[240:243], v[200:203], v[26:29]
	v_mfma_f32_16x16x32_bf16 v[22:25], v[232:235], v[208:211], v[22:25]
	v_mfma_f32_16x16x32_bf16 v[18:21], v[240:243], v[208:211], v[18:21]
	v_mfma_f32_16x16x32_bf16 v[14:17], v[232:235], v[216:219], v[14:17]
	v_mfma_f32_16x16x32_bf16 v[10:13], v[240:243], v[216:219], v[10:13]
	v_mfma_f32_16x16x32_bf16 v[6:9], v[232:235], v[224:227], v[6:9]
	v_mfma_f32_16x16x32_bf16 v[2:5], v[240:243], v[224:227], v[2:5]
	s_barrier
	ds_read_b128 v[176:179], v173
	ds_read_b128 v[180:183], v173 offset:1024
	ds_read_b128 v[184:187], v173 offset:2048
	ds_read_b128 v[188:191], v173 offset:3072
	v_readfirstlane_b32 s4, v165
	v_lshl_add_u64 v[228:229], v[196:197], 0, s[62:63]
	s_mov_b32 m0, s4
	v_readfirstlane_b32 s4, v166
	ds_read_b128 v[192:195], v168 offset:32768
	ds_read_b128 v[200:203], v168 offset:33792
	ds_read_b128 v[204:207], v169 offset:32768
	ds_read_b128 v[208:211], v169 offset:33792
	ds_read_b128 v[212:215], v170 offset:32768
	ds_read_b128 v[216:219], v170 offset:33792
	ds_read_b128 v[220:223], v171 offset:32768
	ds_read_b128 v[224:227], v171 offset:33792
	global_load_lds_dwordx4 v[228:229], off
	v_lshl_add_u64 v[228:229], v[244:245], 0, s[62:63]
	s_mov_b32 m0, s4
	s_nop 0
	global_load_lds_dwordx4 v[228:229], off
	s_waitcnt lgkmcnt(8)
	s_barrier
	s_waitcnt lgkmcnt(0)
	s_waitcnt lgkmcnt(0)
	v_mfma_f32_16x16x32_bf16 v[126:129], v[176:179], v[192:195], v[126:129]
	v_mfma_f32_16x16x32_bf16 v[122:125], v[184:187], v[192:195], v[122:125]
	v_mfma_f32_16x16x32_bf16 v[118:121], v[176:179], v[204:207], v[118:121]
	v_mfma_f32_16x16x32_bf16 v[114:117], v[184:187], v[204:207], v[114:117]
	v_mfma_f32_16x16x32_bf16 v[110:113], v[176:179], v[212:215], v[110:113]
	v_mfma_f32_16x16x32_bf16 v[106:109], v[184:187], v[212:215], v[106:109]
	v_mfma_f32_16x16x32_bf16 v[102:105], v[176:179], v[220:223], v[102:105]
	v_mfma_f32_16x16x32_bf16 v[98:101], v[184:187], v[220:223], v[98:101]
	v_mfma_f32_16x16x32_bf16 v[126:129], v[180:183], v[200:203], v[126:129]
	v_mfma_f32_16x16x32_bf16 v[122:125], v[188:191], v[200:203], v[122:125]
	v_mfma_f32_16x16x32_bf16 v[118:121], v[180:183], v[208:211], v[118:121]
	v_mfma_f32_16x16x32_bf16 v[114:117], v[188:191], v[208:211], v[114:117]
	v_mfma_f32_16x16x32_bf16 v[110:113], v[180:183], v[216:219], v[110:113]
	v_mfma_f32_16x16x32_bf16 v[106:109], v[188:191], v[216:219], v[106:109]
	v_mfma_f32_16x16x32_bf16 v[102:105], v[180:183], v[224:227], v[102:105]
	v_mfma_f32_16x16x32_bf16 v[98:101], v[188:191], v[224:227], v[98:101]
	s_barrier
	v_readfirstlane_b32 s4, v134
	v_lshl_add_u64 v[250:251], v[246:247], 0, s[66:67]
	s_mov_b32 m0, s4
	v_readfirstlane_b32 s4, v152
	ds_read_b128 v[228:231], v174
	ds_read_b128 v[232:235], v174 offset:1024
	ds_read_b128 v[236:239], v174 offset:2048
	ds_read_b128 v[240:243], v174 offset:3072
	global_load_lds_dwordx4 v[250:251], off
	v_lshl_add_u64 v[250:251], v[248:249], 0, s[66:67]
	s_mov_b32 m0, s4
	s_nop 0
	global_load_lds_dwordx4 v[250:251], off
	s_barrier
	s_waitcnt lgkmcnt(0)
	s_waitcnt lgkmcnt(0)
	v_mfma_f32_16x16x32_bf16 v[94:97], v[228:231], v[192:195], v[94:97]
	v_mfma_f32_16x16x32_bf16 v[90:93], v[236:239], v[192:195], v[90:93]
	v_mfma_f32_16x16x32_bf16 v[86:89], v[228:231], v[204:207], v[86:89]
	v_mfma_f32_16x16x32_bf16 v[82:85], v[236:239], v[204:207], v[82:85]
	v_mfma_f32_16x16x32_bf16 v[78:81], v[228:231], v[212:215], v[78:81]
	v_mfma_f32_16x16x32_bf16 v[74:77], v[236:239], v[212:215], v[74:77]
	v_mfma_f32_16x16x32_bf16 v[70:73], v[228:231], v[220:223], v[70:73]
	v_mfma_f32_16x16x32_bf16 v[66:69], v[236:239], v[220:223], v[66:69]
	v_mfma_f32_16x16x32_bf16 v[94:97], v[232:235], v[200:203], v[94:97]
	v_mfma_f32_16x16x32_bf16 v[90:93], v[240:243], v[200:203], v[90:93]
	v_mfma_f32_16x16x32_bf16 v[86:89], v[232:235], v[208:211], v[86:89]
	v_mfma_f32_16x16x32_bf16 v[82:85], v[240:243], v[208:211], v[82:85]
	v_mfma_f32_16x16x32_bf16 v[78:81], v[232:235], v[216:219], v[78:81]
	v_mfma_f32_16x16x32_bf16 v[74:77], v[240:243], v[216:219], v[74:77]
	v_mfma_f32_16x16x32_bf16 v[70:73], v[232:235], v[224:227], v[70:73]
	v_mfma_f32_16x16x32_bf16 v[66:69], v[240:243], v[224:227], v[66:69]
	v_readfirstlane_b32 s4, v153
	v_lshl_add_u64 v[196:197], v[196:197], 0, s[68:69]
	s_mov_b32 m0, s4
	v_readfirstlane_b32 s4, v154
	s_barrier
	ds_read_b128 v[192:195], v168 offset:49152
	ds_read_b128 v[200:203], v168 offset:50176
	ds_read_b128 v[204:207], v169 offset:49152
	ds_read_b128 v[208:211], v169 offset:50176
	ds_read_b128 v[212:215], v170 offset:49152
	ds_read_b128 v[216:219], v170 offset:50176
	ds_read_b128 v[220:223], v171 offset:49152
	ds_read_b128 v[224:227], v171 offset:50176
	global_load_lds_dwordx4 v[196:197], off
	v_lshl_add_u64 v[196:197], v[244:245], 0, s[68:69]
	s_mov_b32 m0, s4
	s_nop 0
	global_load_lds_dwordx4 v[196:197], off
	s_barrier
	s_waitcnt lgkmcnt(0)
	s_waitcnt lgkmcnt(0)
	v_mfma_f32_16x16x32_bf16 v[62:65], v[176:179], v[192:195], v[62:65]
	v_mfma_f32_16x16x32_bf16 v[58:61], v[184:187], v[192:195], v[58:61]
	v_mfma_f32_16x16x32_bf16 v[54:57], v[176:179], v[204:207], v[54:57]
	v_mfma_f32_16x16x32_bf16 v[50:53], v[184:187], v[204:207], v[50:53]
	v_mfma_f32_16x16x32_bf16 v[46:49], v[176:179], v[212:215], v[46:49]
	v_mfma_f32_16x16x32_bf16 v[42:45], v[184:187], v[212:215], v[42:45]
	v_mfma_f32_16x16x32_bf16 v[38:41], v[176:179], v[220:223], v[38:41]
	v_mfma_f32_16x16x32_bf16 v[34:37], v[184:187], v[220:223], v[34:37]
	v_mfma_f32_16x16x32_bf16 v[62:65], v[180:183], v[200:203], v[62:65]
	v_mfma_f32_16x16x32_bf16 v[58:61], v[188:191], v[200:203], v[58:61]
	v_mfma_f32_16x16x32_bf16 v[54:57], v[180:183], v[208:211], v[54:57]
	v_mfma_f32_16x16x32_bf16 v[50:53], v[188:191], v[208:211], v[50:53]
	v_mfma_f32_16x16x32_bf16 v[46:49], v[180:183], v[216:219], v[46:49]
	v_mfma_f32_16x16x32_bf16 v[42:45], v[188:191], v[216:219], v[42:45]
	v_mfma_f32_16x16x32_bf16 v[38:41], v[180:183], v[224:227], v[38:41]
	v_mfma_f32_16x16x32_bf16 v[34:37], v[188:191], v[224:227], v[34:37]
	s_barrier
	v_readfirstlane_b32 s4, v155
	v_lshl_add_u64 v[176:177], v[246:247], 0, s[70:71]
	s_mov_b32 m0, s4
	v_readfirstlane_b32 s4, v156
	global_load_lds_dwordx4 v[176:177], off
	v_lshl_add_u64 v[176:177], v[248:249], 0, s[70:71]
	s_mov_b32 m0, s4
	s_nop 0
	global_load_lds_dwordx4 v[176:177], off
	s_waitcnt vmcnt(6)
	s_barrier
	v_mfma_f32_16x16x32_bf16 v[30:33], v[228:231], v[192:195], v[30:33]
	v_mfma_f32_16x16x32_bf16 v[26:29], v[236:239], v[192:195], v[26:29]
	v_mfma_f32_16x16x32_bf16 v[22:25], v[228:231], v[204:207], v[22:25]
	v_mfma_f32_16x16x32_bf16 v[18:21], v[236:239], v[204:207], v[18:21]
	v_mfma_f32_16x16x32_bf16 v[14:17], v[228:231], v[212:215], v[14:17]
	v_mfma_f32_16x16x32_bf16 v[10:13], v[236:239], v[212:215], v[10:13]
	v_mfma_f32_16x16x32_bf16 v[6:9], v[228:231], v[220:223], v[6:9]
	v_mfma_f32_16x16x32_bf16 v[2:5], v[236:239], v[220:223], v[2:5]
	v_mfma_f32_16x16x32_bf16 v[30:33], v[232:235], v[200:203], v[30:33]
	v_mfma_f32_16x16x32_bf16 v[26:29], v[240:243], v[200:203], v[26:29]
	v_mfma_f32_16x16x32_bf16 v[22:25], v[232:235], v[208:211], v[22:25]
	v_mfma_f32_16x16x32_bf16 v[18:21], v[240:243], v[208:211], v[18:21]
	v_mfma_f32_16x16x32_bf16 v[14:17], v[232:235], v[216:219], v[14:17]
	v_mfma_f32_16x16x32_bf16 v[10:13], v[240:243], v[216:219], v[10:13]
	v_mfma_f32_16x16x32_bf16 v[6:9], v[232:235], v[224:227], v[6:9]
	v_mfma_f32_16x16x32_bf16 v[2:5], v[240:243], v[224:227], v[2:5]
	s_add_i32 s1, s1, 2
	s_add_u32 s10, s10, 0x100
	s_addc_u32 s11, s11, 0
	s_cmp_lt_u32 s1, 12
	s_barrier
	s_cbranch_scc1 .LBB0_171
	v_readfirstlane_b32 s1, v157
	v_lshl_add_u64 v[140:141], v[140:141], 0, s[78:79]
	s_mov_b32 m0, s1
	v_readfirstlane_b32 s1, v175
	ds_read_b128 v[144:147], v167
	ds_read_b128 v[148:151], v167 offset:1024
	ds_read_b128 v[152:155], v167 offset:2048
	ds_read_b128 v[176:179], v167 offset:3072
	ds_read_b128 v[180:183], v168
	ds_read_b128 v[184:187], v168 offset:1024
	ds_read_b128 v[188:191], v169
	ds_read_b128 v[192:195], v169 offset:1024
	ds_read_b128 v[200:203], v170
	ds_read_b128 v[204:207], v170 offset:1024
	ds_read_b128 v[208:211], v171
	ds_read_b128 v[212:215], v171 offset:1024
	global_load_lds_dwordx4 v[140:141], off
	v_lshl_add_u64 v[140:141], v[142:143], 0, s[78:79]
	s_mov_b32 m0, s1
	s_nop 0
	global_load_lds_dwordx4 v[140:141], off
	s_barrier
	s_waitcnt lgkmcnt(0)
	s_waitcnt lgkmcnt(0)
	v_mfma_f32_16x16x32_bf16 v[126:129], v[144:147], v[180:183], v[126:129]
	v_mfma_f32_16x16x32_bf16 v[122:125], v[152:155], v[180:183], v[122:125]
	v_mfma_f32_16x16x32_bf16 v[118:121], v[144:147], v[188:191], v[118:121]
	v_mfma_f32_16x16x32_bf16 v[114:117], v[152:155], v[188:191], v[114:117]
	v_mfma_f32_16x16x32_bf16 v[102:105], v[144:147], v[208:211], v[102:105]
	v_mfma_f32_16x16x32_bf16 v[98:101], v[152:155], v[208:211], v[98:101]
	v_mfma_f32_16x16x32_bf16 v[126:129], v[148:151], v[184:187], v[126:129]
	v_mfma_f32_16x16x32_bf16 v[122:125], v[176:179], v[184:187], v[122:125]
	v_mfma_f32_16x16x32_bf16 v[118:121], v[148:151], v[192:195], v[118:121]
	v_mfma_f32_16x16x32_bf16 v[114:117], v[176:179], v[192:195], v[114:117]
	v_mfma_f32_16x16x32_bf16 v[110:113], v[144:147], v[200:203], v[110:113]
	v_mfma_f32_16x16x32_bf16 v[106:109], v[152:155], v[200:203], v[106:109]
	v_mfma_f32_16x16x32_bf16 v[102:105], v[148:151], v[212:215], v[102:105]
	v_mfma_f32_16x16x32_bf16 v[98:101], v[176:179], v[212:215], v[98:101]
	v_mfma_f32_16x16x32_bf16 v[140:143], v[148:151], v[204:207], v[110:113]
	v_mfma_f32_16x16x32_bf16 v[216:219], v[176:179], v[204:207], v[106:109]
	s_barrier
	s_nop 1
	ds_read_b128 v[106:109], v172
	ds_read_b128 v[110:113], v172 offset:1024
	ds_read_b128 v[220:223], v172 offset:2048
	ds_read_b128 v[224:227], v172 offset:3072
	s_barrier
	s_waitcnt lgkmcnt(0)
	s_waitcnt lgkmcnt(0)
	v_mfma_f32_16x16x32_bf16 v[86:89], v[106:109], v[188:191], v[86:89]
	v_mfma_f32_16x16x32_bf16 v[82:85], v[220:223], v[188:191], v[82:85]
	v_mfma_f32_16x16x32_bf16 v[70:73], v[106:109], v[208:211], v[70:73]
	v_mfma_f32_16x16x32_bf16 v[66:69], v[220:223], v[208:211], v[66:69]
	v_mfma_f32_16x16x32_bf16 v[94:97], v[106:109], v[180:183], v[94:97]
	v_mfma_f32_16x16x32_bf16 v[90:93], v[220:223], v[180:183], v[90:93]
	v_mfma_f32_16x16x32_bf16 v[86:89], v[110:113], v[192:195], v[86:89]
	v_mfma_f32_16x16x32_bf16 v[82:85], v[224:227], v[192:195], v[82:85]
	v_mfma_f32_16x16x32_bf16 v[78:81], v[106:109], v[200:203], v[78:81]
	v_mfma_f32_16x16x32_bf16 v[74:77], v[220:223], v[200:203], v[74:77]
	v_mfma_f32_16x16x32_bf16 v[70:73], v[110:113], v[212:215], v[70:73]
	v_mfma_f32_16x16x32_bf16 v[66:69], v[224:227], v[212:215], v[66:69]
	v_mfma_f32_16x16x32_bf16 v[228:231], v[110:113], v[184:187], v[94:97]
	v_mfma_f32_16x16x32_bf16 v[180:183], v[224:227], v[184:187], v[90:93]
	v_mfma_f32_16x16x32_bf16 v[184:187], v[110:113], v[204:207], v[78:81]
	v_mfma_f32_16x16x32_bf16 v[188:191], v[224:227], v[204:207], v[74:77]
	s_barrier
	s_nop 0
	ds_read_b128 v[74:77], v168 offset:16384
	ds_read_b128 v[78:81], v168 offset:17408
	ds_read_b128 v[90:93], v169 offset:16384
	ds_read_b128 v[94:97], v169 offset:17408
	ds_read_b128 v[192:195], v170 offset:16384
	ds_read_b128 v[200:203], v170 offset:17408
	ds_read_b128 v[204:207], v171 offset:16384
	ds_read_b128 v[208:211], v171 offset:17408
	s_waitcnt vmcnt(4)
	s_barrier
	s_waitcnt lgkmcnt(0)
	s_waitcnt lgkmcnt(0)
	v_mfma_f32_16x16x32_bf16 v[62:65], v[144:147], v[74:77], v[62:65]
	v_mfma_f32_16x16x32_bf16 v[58:61], v[152:155], v[74:77], v[58:61]
	v_mfma_f32_16x16x32_bf16 v[54:57], v[144:147], v[90:93], v[54:57]
	v_mfma_f32_16x16x32_bf16 v[50:53], v[152:155], v[90:93], v[50:53]
	v_mfma_f32_16x16x32_bf16 v[38:41], v[144:147], v[204:207], v[38:41]
	v_mfma_f32_16x16x32_bf16 v[34:37], v[152:155], v[204:207], v[34:37]
	v_mfma_f32_16x16x32_bf16 v[62:65], v[148:151], v[78:81], v[62:65]
	v_mfma_f32_16x16x32_bf16 v[58:61], v[176:179], v[78:81], v[58:61]
	v_mfma_f32_16x16x32_bf16 v[54:57], v[148:151], v[94:97], v[54:57]
	v_mfma_f32_16x16x32_bf16 v[50:53], v[176:179], v[94:97], v[50:53]
	v_mfma_f32_16x16x32_bf16 v[46:49], v[144:147], v[192:195], v[46:49]
	v_mfma_f32_16x16x32_bf16 v[42:45], v[152:155], v[192:195], v[42:45]
	v_mfma_f32_16x16x32_bf16 v[38:41], v[148:151], v[208:211], v[38:41]
	v_mfma_f32_16x16x32_bf16 v[34:37], v[176:179], v[208:211], v[34:37]
	v_mfma_f32_16x16x32_bf16 v[212:215], v[148:151], v[200:203], v[46:49]
	v_mfma_f32_16x16x32_bf16 v[232:235], v[176:179], v[200:203], v[42:45]
	v_mfma_f32_16x16x32_bf16 v[22:25], v[106:109], v[90:93], v[22:25]
	v_mfma_f32_16x16x32_bf16 v[18:21], v[220:223], v[90:93], v[18:21]
	v_mfma_f32_16x16x32_bf16 v[6:9], v[106:109], v[204:207], v[6:9]
	v_mfma_f32_16x16x32_bf16 v[2:5], v[220:223], v[204:207], v[2:5]
	v_mfma_f32_16x16x32_bf16 v[30:33], v[106:109], v[74:77], v[30:33]
	v_mfma_f32_16x16x32_bf16 v[26:29], v[220:223], v[74:77], v[26:29]
	v_mfma_f32_16x16x32_bf16 v[22:25], v[110:113], v[94:97], v[22:25]
	v_mfma_f32_16x16x32_bf16 v[18:21], v[224:227], v[94:97], v[18:21]
	v_mfma_f32_16x16x32_bf16 v[14:17], v[106:109], v[192:195], v[14:17]
	v_mfma_f32_16x16x32_bf16 v[10:13], v[220:223], v[192:195], v[10:13]
	v_mfma_f32_16x16x32_bf16 v[6:9], v[110:113], v[208:211], v[6:9]
	v_mfma_f32_16x16x32_bf16 v[2:5], v[224:227], v[208:211], v[2:5]
	v_mfma_f32_16x16x32_bf16 v[144:147], v[110:113], v[78:81], v[30:33]
	v_mfma_f32_16x16x32_bf16 v[148:151], v[224:227], v[78:81], v[26:29]
	v_mfma_f32_16x16x32_bf16 v[152:155], v[110:113], v[200:203], v[14:17]
	v_mfma_f32_16x16x32_bf16 v[176:179], v[224:227], v[200:203], v[10:13]
	s_barrier
	s_nop 0
	ds_read_b128 v[10:13], v173
	ds_read_b128 v[14:17], v173 offset:1024
	ds_read_b128 v[192:195], v173 offset:2048
	ds_read_b128 v[200:203], v173 offset:3072
	ds_read_b128 v[26:29], v168 offset:32768
	ds_read_b128 v[30:33], v168 offset:33792
	ds_read_b128 v[42:45], v169 offset:32768
	ds_read_b128 v[46:49], v169 offset:33792
	ds_read_b128 v[204:207], v170 offset:32768
	ds_read_b128 v[208:211], v170 offset:33792
	ds_read_b128 v[220:223], v171 offset:32768
	ds_read_b128 v[224:227], v171 offset:33792
	s_waitcnt vmcnt(2)
	s_barrier
	s_waitcnt lgkmcnt(0)
	s_waitcnt lgkmcnt(0)
	v_mfma_f32_16x16x32_bf16 v[74:77], v[10:13], v[26:29], v[126:129]
	v_mfma_f32_16x16x32_bf16 v[126:129], v[14:17], v[30:33], v[74:77]
	v_mfma_f32_16x16x32_bf16 v[74:77], v[192:195], v[26:29], v[122:125]
	v_mfma_f32_16x16x32_bf16 v[122:125], v[200:203], v[30:33], v[74:77]
	v_mfma_f32_16x16x32_bf16 v[74:77], v[10:13], v[42:45], v[118:121]
	v_mfma_f32_16x16x32_bf16 v[110:113], v[14:17], v[46:49], v[74:77]
	v_mfma_f32_16x16x32_bf16 v[74:77], v[192:195], v[42:45], v[114:117]
	v_mfma_f32_16x16x32_bf16 v[106:109], v[200:203], v[46:49], v[74:77]
	v_mfma_f32_16x16x32_bf16 v[74:77], v[10:13], v[204:207], v[140:143]
	v_mfma_f32_16x16x32_bf16 v[94:97], v[14:17], v[208:211], v[74:77]
	v_mfma_f32_16x16x32_bf16 v[74:77], v[192:195], v[204:207], v[216:219]
	v_mfma_f32_16x16x32_bf16 v[90:93], v[200:203], v[208:211], v[74:77]
	v_mfma_f32_16x16x32_bf16 v[74:77], v[10:13], v[220:223], v[102:105]
	v_mfma_f32_16x16x32_bf16 v[78:81], v[14:17], v[224:227], v[74:77]
	v_mfma_f32_16x16x32_bf16 v[74:77], v[192:195], v[220:223], v[98:101]
	v_mfma_f32_16x16x32_bf16 v[74:77], v[200:203], v[224:227], v[74:77]
	s_barrier
	ds_read_b128 v[140:143], v174
	ds_read_b128 v[216:219], v174 offset:1024
	ds_read_b128 v[236:239], v174 offset:2048
	ds_read_b128 v[240:243], v174 offset:3072
	s_waitcnt vmcnt(0)
	s_barrier
	s_waitcnt lgkmcnt(0)
	s_waitcnt lgkmcnt(0)
	v_mfma_f32_16x16x32_bf16 v[98:101], v[140:143], v[26:29], v[228:231]
	v_mfma_f32_16x16x32_bf16 v[26:29], v[236:239], v[26:29], v[180:183]
	v_mfma_f32_16x16x32_bf16 v[114:117], v[240:243], v[30:33], v[26:29]
	v_mfma_f32_16x16x32_bf16 v[26:29], v[140:143], v[42:45], v[86:89]
	v_mfma_f32_16x16x32_bf16 v[102:105], v[216:219], v[46:49], v[26:29]
	v_mfma_f32_16x16x32_bf16 v[26:29], v[236:239], v[42:45], v[82:85]
	v_mfma_f32_16x16x32_bf16 v[118:121], v[216:219], v[30:33], v[98:101]
	v_mfma_f32_16x16x32_bf16 v[98:101], v[240:243], v[46:49], v[26:29]
	v_mfma_f32_16x16x32_bf16 v[26:29], v[140:143], v[204:207], v[184:187]
	v_mfma_f32_16x16x32_bf16 v[86:89], v[216:219], v[208:211], v[26:29]
	v_mfma_f32_16x16x32_bf16 v[26:29], v[236:239], v[204:207], v[188:191]
	v_mfma_f32_16x16x32_bf16 v[82:85], v[240:243], v[208:211], v[26:29]
	v_mfma_f32_16x16x32_bf16 v[26:29], v[140:143], v[220:223], v[70:73]
	v_mfma_f32_16x16x32_bf16 v[70:73], v[216:219], v[224:227], v[26:29]
	v_mfma_f32_16x16x32_bf16 v[26:29], v[236:239], v[220:223], v[66:69]
	v_mfma_f32_16x16x32_bf16 v[66:69], v[240:243], v[224:227], v[26:29]
	s_barrier
	ds_read_b128 v[180:183], v168 offset:49152
	ds_read_b128 v[184:187], v168 offset:50176
	ds_read_b128 v[188:191], v169 offset:49152
	ds_read_b128 v[204:207], v169 offset:50176
	ds_read_b128 v[208:211], v170 offset:49152
	ds_read_b128 v[220:223], v170 offset:50176
	ds_read_b128 v[224:227], v171 offset:49152
	ds_read_b128 v[228:231], v171 offset:50176
	s_barrier
	s_waitcnt lgkmcnt(0)
	s_waitcnt lgkmcnt(0)
	v_mfma_f32_16x16x32_bf16 v[26:29], v[10:13], v[180:183], v[62:65]
	v_mfma_f32_16x16x32_bf16 v[62:65], v[14:17], v[184:187], v[26:29]
	v_mfma_f32_16x16x32_bf16 v[26:29], v[192:195], v[180:183], v[58:61]
	v_mfma_f32_16x16x32_bf16 v[58:61], v[200:203], v[184:187], v[26:29]
	v_mfma_f32_16x16x32_bf16 v[26:29], v[10:13], v[188:191], v[54:57]
	v_mfma_f32_16x16x32_bf16 v[46:49], v[14:17], v[204:207], v[26:29]
	v_mfma_f32_16x16x32_bf16 v[26:29], v[192:195], v[188:191], v[50:53]
	v_mfma_f32_16x16x32_bf16 v[42:45], v[200:203], v[204:207], v[26:29]
	v_mfma_f32_16x16x32_bf16 v[26:29], v[10:13], v[208:211], v[212:215]
	v_mfma_f32_16x16x32_bf16 v[10:13], v[10:13], v[224:227], v[38:41]
	v_mfma_f32_16x16x32_bf16 v[30:33], v[14:17], v[220:223], v[26:29]
	v_mfma_f32_16x16x32_bf16 v[26:29], v[192:195], v[208:211], v[232:235]
	v_mfma_f32_16x16x32_bf16 v[14:17], v[14:17], v[228:231], v[10:13]
	v_mfma_f32_16x16x32_bf16 v[10:13], v[192:195], v[224:227], v[34:37]
	v_mfma_f32_16x16x32_bf16 v[26:29], v[200:203], v[220:223], v[26:29]
	v_mfma_f32_16x16x32_bf16 v[10:13], v[200:203], v[228:231], v[10:13]
	v_mfma_f32_16x16x32_bf16 v[34:37], v[140:143], v[180:183], v[144:147]
	v_mfma_f32_16x16x32_bf16 v[54:57], v[216:219], v[184:187], v[34:37]
	v_mfma_f32_16x16x32_bf16 v[34:37], v[236:239], v[180:183], v[148:151]
	v_mfma_f32_16x16x32_bf16 v[18:21], v[236:239], v[188:191], v[18:21]
	v_mfma_f32_16x16x32_bf16 v[50:53], v[240:243], v[184:187], v[34:37]
	v_mfma_f32_16x16x32_bf16 v[22:25], v[140:143], v[188:191], v[22:25]
	v_mfma_f32_16x16x32_bf16 v[34:37], v[240:243], v[204:207], v[18:21]
	v_mfma_f32_16x16x32_bf16 v[18:21], v[140:143], v[208:211], v[152:155]
	v_mfma_f32_16x16x32_bf16 v[38:41], v[216:219], v[204:207], v[22:25]
	v_mfma_f32_16x16x32_bf16 v[22:25], v[216:219], v[220:223], v[18:21]
	v_mfma_f32_16x16x32_bf16 v[18:21], v[236:239], v[208:211], v[176:179]
	v_mfma_f32_16x16x32_bf16 v[6:9], v[140:143], v[224:227], v[6:9]
	v_mfma_f32_16x16x32_bf16 v[2:5], v[236:239], v[224:227], v[2:5]
	v_mfma_f32_16x16x32_bf16 v[18:21], v[240:243], v[220:223], v[18:21]
	v_mfma_f32_16x16x32_bf16 v[6:9], v[216:219], v[228:231], v[6:9]
	v_mfma_f32_16x16x32_bf16 v[2:5], v[240:243], v[228:231], v[2:5]
	s_barrier
	s_and_saveexec_b64 s[4:5], s[74:75]
	s_cbranch_execz .LBB0_174
	s_barrier
.LBB0_174:
	s_setprio 0
	s_or_b64 exec, exec, s[4:5]
	v_and_b32_e32 v134, 63, v0
	v_lshrrev_b32_e32 v156, 6, v0
	v_and_b32_e32 v191, 15, v134
	v_lshrrev_b32_e32 v192, 4, v134
	v_readfirstlane_b32 s4, v156
	s_lshr_b32 s5, s4, 2
	s_and_b32 s6, s4, 3
	s_mul_i32 s7, s4, 0x2400
	s_add_i32 s7, s7, 16
	v_mul_u32_u24_e32 v175, 0x50, v191
	v_lshl_add_u32 v175, v192, 3, v175
	v_add_u32_e32 v175, s7, v175
	v_lshrrev_b32_e32 v156, 2, v134
	v_and_b32_e32 v157, 3, v134
	v_mul_u32_u24_e32 v176, 0x50, v156
	v_lshl_add_u32 v176, v157, 4, v176
	v_add_u32_e32 v176, s7, v176
	v_mul_u32_u24_e32 v177, 0x90, v191
	v_lshl_add_u32 v177, v192, 4, v177
	v_add_u32_e32 v177, s7, v177
	v_lshrrev_b32_e32 v193, 3, v134
	v_and_b32_e32 v194, 7, v134
	v_mul_u32_u24_e32 v178, 0x90, v193
	v_lshl_add_u32 v178, v194, 4, v178
	v_add_u32_e32 v178, s7, v178
	v_lshlrev_b32_e32 v183, 11, v193
	v_lshl_add_u32 v183, v194, 4, v183
	v_add_u32_e32 v184, 0x4000, v183
	v_add_u32_e32 v185, 0x8000, v183
	v_add_u32_e32 v186, 0xc000, v183
	v_add_u32_e32 v187, 0x10000, v183
	v_add_u32_e32 v188, 0x14000, v183
	v_add_u32_e32 v189, 0x18000, v183
	v_add_u32_e32 v190, 0x1c000, v183
	s_lshr_b32 s11, s0, 8
	s_mov_b32 s14, 10
	s_mov_b32 s30, 0
	s_mov_b32 s31, 0
	s_cmp_gt_u32 s11, 1
	s_cbranch_scc1 .Lp1e_t1
	s_mov_b64 s[12:13], s[56:57]
	s_mov_b32 s15, 0
	s_branch .Lp1e_tdone

.LBB0_2244:
	s_ashr_i32 s8, s34, 3
	s_add_i32 s8, s36, s8
	s_ashr_i32 s9, s8, 31
	s_lshr_b32 s9, s9, 27
	s_add_i32 s9, s8, s9
	s_and_b32 s34, s9, 0xffe0
	s_sub_i32 s8, s8, s34
	s_bfe_i32 s34, s8, 0x80000
	s_bfe_u32 s34, s34, 0x3000c
	s_add_i32 s34, s8, s34
	s_bfe_i32 s35, s34, 0x80000
	s_and_b32 s34, s34, 0xf8
	s_sub_i32 s8, s8, s34
	s_sext_i32_i8 s8, s8
	s_lshl_b32 s9, s9, 6
	s_sext_i32_i16 s35, s35
	s_and_b32 s9, s9, 0xfffff800
	s_lshl_b32 s8, s8, 8
	s_add_i32 s34, s8, s9
	s_lshl_b32 s8, s35, 5
	s_and_b32 s8, s8, 0xffffff00
	s_ashr_i32 s9, s8, 31
	s_lshl_b64 s[36:37], s[8:9], 11
	s_add_u32 s38, s10, s36
	s_addc_u32 s39, s11, s37
	s_ashr_i32 s35, s34, 31
	v_lshl_add_u64 v[4:5], s[38:39], 0, v[132:133]
	s_waitcnt lgkmcnt(0)
	v_lshl_add_u64 v[2:3], s[38:39], 0, v[130:131]
	s_lshl_b64 s[38:39], s[34:35], 11
	s_add_u32 s58, s40, s38
	s_addc_u32 s59, s41, s39
	v_lshl_add_u64 v[8:9], s[58:59], 0, v[132:133]
	v_lshl_add_u64 v[6:7], s[58:59], 0, v[130:131]
	s_or_b32 s58, s8, 0x80
	s_ashr_i32 s59, s58, 31
	s_lshl_b64 s[58:59], s[58:59], 11
	v_readfirstlane_b32 s9, v153
	s_add_u32 s58, s10, s58
	s_mov_b32 m0, s9
	v_readfirstlane_b32 s9, v154
	s_addc_u32 s59, s11, s59
	global_load_lds_dwordx4 v[4:5], off
	s_mov_b32 m0, s9
	v_readfirstlane_b32 s9, v155
	v_lshl_add_u64 v[12:13], s[58:59], 0, v[132:133]
	v_lshl_add_u64 v[10:11], s[58:59], 0, v[130:131]
	s_or_b32 s58, s34, 0x80
	global_load_lds_dwordx4 v[2:3], off
	s_mov_b32 m0, s9
	v_readfirstlane_b32 s9, v156
	s_ashr_i32 s59, s58, 31
	global_load_lds_dwordx4 v[8:9], off
	s_mov_b32 m0, s9
	v_readfirstlane_b32 s9, v157
	s_lshl_b64 s[58:59], s[58:59], 11
	global_load_lds_dwordx4 v[6:7], off
	s_mov_b32 m0, s9
	v_readfirstlane_b32 s9, v158
	s_add_u32 s58, s40, s58
	global_load_lds_dwordx4 v[12:13], off
	s_mov_b32 m0, s9
	s_addc_u32 s59, s41, s59
	v_readfirstlane_b32 s9, v159
	global_load_lds_dwordx4 v[10:11], off
	v_lshl_add_u64 v[140:141], s[58:59], 0, v[132:133]
	s_mov_b32 m0, s9
	v_readfirstlane_b32 s9, v160
	global_load_lds_dwordx4 v[140:141], off
	v_lshl_add_u64 v[142:143], s[58:59], 0, v[130:131]
	s_mov_b32 m0, s9
	s_nop 0
	global_load_lds_dwordx4 v[142:143], off
	s_and_saveexec_b64 s[58:59], s[0:1]
	s_cbranch_execz .LBB0_2246
	s_barrier
	s_setprio 1

.LBB0_2247:
	ds_read_b128 v[178:181], v162
	ds_read_b128 v[182:185], v162 offset:1024
	ds_read_b128 v[186:189], v162 offset:2048
	ds_read_b128 v[190:193], v162 offset:3072
	v_add_u32_e32 v175, 0xc000, v155
	v_lshl_add_u64 v[244:245], s[36:37], 0, v[148:149]
	v_readfirstlane_b32 s35, v175
	v_lshl_add_u64 v[176:177], v[244:245], 0, s[14:15]
	s_mov_b32 m0, s35
	ds_read_b128 v[194:197], v163
	ds_read_b128 v[200:203], v163 offset:1024
	ds_read_b128 v[204:207], v164
	ds_read_b128 v[208:211], v164 offset:1024
	ds_read_b128 v[212:215], v165
	ds_read_b128 v[216:219], v165 offset:1024
	ds_read_b128 v[220:223], v166
	ds_read_b128 v[224:227], v166 offset:1024
	global_load_lds_dwordx4 v[176:177], off
	v_add_u32_e32 v176, 0xe000, v155
	v_lshl_add_u64 v[246:247], s[36:37], 0, v[150:151]
	v_readfirstlane_b32 s35, v176
	v_lshl_add_u64 v[228:229], v[246:247], 0, s[14:15]
	s_mov_b32 m0, s35
	s_nop 0
	global_load_lds_dwordx4 v[228:229], off
	s_waitcnt lgkmcnt(8)
	s_barrier
	s_waitcnt lgkmcnt(0)
	s_waitcnt lgkmcnt(0)
	v_mfma_f32_16x16x32_bf16 v[126:129], v[178:181], v[194:197], v[126:129]
	v_mfma_f32_16x16x32_bf16 v[122:125], v[186:189], v[194:197], v[122:125]
	v_mfma_f32_16x16x32_bf16 v[118:121], v[178:181], v[204:207], v[118:121]
	v_mfma_f32_16x16x32_bf16 v[114:117], v[186:189], v[204:207], v[114:117]
	v_mfma_f32_16x16x32_bf16 v[110:113], v[178:181], v[212:215], v[110:113]
	v_mfma_f32_16x16x32_bf16 v[106:109], v[186:189], v[212:215], v[106:109]
	v_mfma_f32_16x16x32_bf16 v[102:105], v[178:181], v[220:223], v[102:105]
	v_mfma_f32_16x16x32_bf16 v[98:101], v[186:189], v[220:223], v[98:101]
	v_mfma_f32_16x16x32_bf16 v[126:129], v[182:185], v[200:203], v[126:129]
	v_mfma_f32_16x16x32_bf16 v[122:125], v[190:193], v[200:203], v[122:125]
	v_mfma_f32_16x16x32_bf16 v[118:121], v[182:185], v[208:211], v[118:121]
	v_mfma_f32_16x16x32_bf16 v[114:117], v[190:193], v[208:211], v[114:117]
	v_mfma_f32_16x16x32_bf16 v[110:113], v[182:185], v[216:219], v[110:113]
	v_mfma_f32_16x16x32_bf16 v[106:109], v[190:193], v[216:219], v[106:109]
	v_mfma_f32_16x16x32_bf16 v[102:105], v[182:185], v[224:227], v[102:105]
	v_mfma_f32_16x16x32_bf16 v[98:101], v[190:193], v[224:227], v[98:101]
	s_barrier
	v_lshl_add_u64 v[248:249], s[36:37], 0, v[144:145]
	v_readfirstlane_b32 s35, v153
	v_lshl_add_u64 v[250:251], v[248:249], 0, s[16:17]
	s_mov_b32 m0, s35
	ds_read_b128 v[228:231], v167
	ds_read_b128 v[232:235], v167 offset:1024
	ds_read_b128 v[236:239], v167 offset:2048
	ds_read_b128 v[240:243], v167 offset:3072
	global_load_lds_dwordx4 v[250:251], off
	v_lshl_add_u64 v[250:251], s[36:37], 0, v[146:147]
	v_readfirstlane_b32 s35, v154
	v_lshl_add_u64 v[252:253], v[250:251], 0, s[16:17]
	s_mov_b32 m0, s35
	s_nop 0
	global_load_lds_dwordx4 v[252:253], off
	s_barrier
	s_waitcnt lgkmcnt(0)
	s_waitcnt lgkmcnt(0)
	v_mfma_f32_16x16x32_bf16 v[94:97], v[228:231], v[194:197], v[94:97]
	v_mfma_f32_16x16x32_bf16 v[90:93], v[236:239], v[194:197], v[90:93]
	v_mfma_f32_16x16x32_bf16 v[86:89], v[228:231], v[204:207], v[86:89]
	v_mfma_f32_16x16x32_bf16 v[82:85], v[236:239], v[204:207], v[82:85]
	v_mfma_f32_16x16x32_bf16 v[78:81], v[228:231], v[212:215], v[78:81]
	v_mfma_f32_16x16x32_bf16 v[74:77], v[236:239], v[212:215], v[74:77]
	v_mfma_f32_16x16x32_bf16 v[70:73], v[228:231], v[220:223], v[70:73]
	v_mfma_f32_16x16x32_bf16 v[66:69], v[236:239], v[220:223], v[66:69]
	v_mfma_f32_16x16x32_bf16 v[94:97], v[232:235], v[200:203], v[94:97]
	v_mfma_f32_16x16x32_bf16 v[90:93], v[240:243], v[200:203], v[90:93]
	v_mfma_f32_16x16x32_bf16 v[86:89], v[232:235], v[208:211], v[86:89]
	v_mfma_f32_16x16x32_bf16 v[82:85], v[240:243], v[208:211], v[82:85]
	v_mfma_f32_16x16x32_bf16 v[78:81], v[232:235], v[216:219], v[78:81]
	v_mfma_f32_16x16x32_bf16 v[74:77], v[240:243], v[216:219], v[74:77]
	v_mfma_f32_16x16x32_bf16 v[70:73], v[232:235], v[224:227], v[70:73]
	v_mfma_f32_16x16x32_bf16 v[66:69], v[240:243], v[224:227], v[66:69]
	v_readfirstlane_b32 s35, v155
	v_lshl_add_u64 v[252:253], v[244:245], 0, s[18:19]
	s_mov_b32 m0, s35
	v_readfirstlane_b32 s35, v156
	s_barrier
	ds_read_b128 v[194:197], v163 offset:16384
	ds_read_b128 v[200:203], v163 offset:17408
	ds_read_b128 v[204:207], v164 offset:16384
	ds_read_b128 v[208:211], v164 offset:17408
	ds_read_b128 v[212:215], v165 offset:16384
	ds_read_b128 v[216:219], v165 offset:17408
	ds_read_b128 v[220:223], v166 offset:16384
	ds_read_b128 v[224:227], v166 offset:17408
	global_load_lds_dwordx4 v[252:253], off
	v_lshl_add_u64 v[252:253], v[246:247], 0, s[18:19]
	s_mov_b32 m0, s35
	s_nop 0
	global_load_lds_dwordx4 v[252:253], off
	s_barrier
	s_waitcnt lgkmcnt(0)
	s_waitcnt lgkmcnt(0)
	v_mfma_f32_16x16x32_bf16 v[62:65], v[178:181], v[194:197], v[62:65]
	v_mfma_f32_16x16x32_bf16 v[58:61], v[186:189], v[194:197], v[58:61]
	v_mfma_f32_16x16x32_bf16 v[54:57], v[178:181], v[204:207], v[54:57]
	v_mfma_f32_16x16x32_bf16 v[50:53], v[186:189], v[204:207], v[50:53]
	v_mfma_f32_16x16x32_bf16 v[46:49], v[178:181], v[212:215], v[46:49]
	v_mfma_f32_16x16x32_bf16 v[42:45], v[186:189], v[212:215], v[42:45]
	v_mfma_f32_16x16x32_bf16 v[38:41], v[178:181], v[220:223], v[38:41]
	v_mfma_f32_16x16x32_bf16 v[34:37], v[186:189], v[220:223], v[34:37]
	v_mfma_f32_16x16x32_bf16 v[62:65], v[182:185], v[200:203], v[62:65]
	v_mfma_f32_16x16x32_bf16 v[58:61], v[190:193], v[200:203], v[58:61]
	v_mfma_f32_16x16x32_bf16 v[54:57], v[182:185], v[208:211], v[54:57]
	v_mfma_f32_16x16x32_bf16 v[50:53], v[190:193], v[208:211], v[50:53]
	v_mfma_f32_16x16x32_bf16 v[46:49], v[182:185], v[216:219], v[46:49]
	v_mfma_f32_16x16x32_bf16 v[42:45], v[190:193], v[216:219], v[42:45]
	v_mfma_f32_16x16x32_bf16 v[38:41], v[182:185], v[224:227], v[38:41]
	v_mfma_f32_16x16x32_bf16 v[34:37], v[190:193], v[224:227], v[34:37]
	s_barrier
	v_readfirstlane_b32 s35, v157
	v_lshl_add_u64 v[178:179], v[248:249], 0, s[20:21]
	s_mov_b32 m0, s35
	v_readfirstlane_b32 s35, v158
	global_load_lds_dwordx4 v[178:179], off
	v_lshl_add_u64 v[178:179], v[250:251], 0, s[20:21]
	s_mov_b32 m0, s35
	s_nop 0
	global_load_lds_dwordx4 v[178:179], off
	s_waitcnt vmcnt(6)
	s_barrier
	v_mfma_f32_16x16x32_bf16 v[30:33], v[228:231], v[194:197], v[30:33]
	v_mfma_f32_16x16x32_bf16 v[26:29], v[236:239], v[194:197], v[26:29]
	v_mfma_f32_16x16x32_bf16 v[22:25], v[228:231], v[204:207], v[22:25]
	v_mfma_f32_16x16x32_bf16 v[18:21], v[236:239], v[204:207], v[18:21]
	v_mfma_f32_16x16x32_bf16 v[14:17], v[228:231], v[212:215], v[14:17]
	v_mfma_f32_16x16x32_bf16 v[10:13], v[236:239], v[212:215], v[10:13]
	v_mfma_f32_16x16x32_bf16 v[6:9], v[228:231], v[220:223], v[6:9]
	v_mfma_f32_16x16x32_bf16 v[2:5], v[236:239], v[220:223], v[2:5]
	v_mfma_f32_16x16x32_bf16 v[30:33], v[232:235], v[200:203], v[30:33]
	v_mfma_f32_16x16x32_bf16 v[26:29], v[240:243], v[200:203], v[26:29]
	v_mfma_f32_16x16x32_bf16 v[22:25], v[232:235], v[208:211], v[22:25]
	v_mfma_f32_16x16x32_bf16 v[18:21], v[240:243], v[208:211], v[18:21]
	v_mfma_f32_16x16x32_bf16 v[14:17], v[232:235], v[216:219], v[14:17]
	v_mfma_f32_16x16x32_bf16 v[10:13], v[240:243], v[216:219], v[10:13]
	v_mfma_f32_16x16x32_bf16 v[6:9], v[232:235], v[224:227], v[6:9]
	v_mfma_f32_16x16x32_bf16 v[2:5], v[240:243], v[224:227], v[2:5]
	s_barrier
	ds_read_b128 v[178:181], v168
	ds_read_b128 v[182:185], v168 offset:1024
	ds_read_b128 v[186:189], v168 offset:2048
	ds_read_b128 v[190:193], v168 offset:3072
	v_readfirstlane_b32 s35, v159
	v_lshl_add_u64 v[228:229], v[244:245], 0, s[22:23]
	s_mov_b32 m0, s35
	v_readfirstlane_b32 s35, v160
	ds_read_b128 v[194:197], v163 offset:32768
	ds_read_b128 v[200:203], v163 offset:33792
	ds_read_b128 v[204:207], v164 offset:32768
	ds_read_b128 v[208:211], v164 offset:33792
	ds_read_b128 v[212:215], v165 offset:32768
	ds_read_b128 v[216:219], v165 offset:33792
	ds_read_b128 v[220:223], v166 offset:32768
	ds_read_b128 v[224:227], v166 offset:33792
	global_load_lds_dwordx4 v[228:229], off
	v_lshl_add_u64 v[228:229], v[246:247], 0, s[22:23]
	s_mov_b32 m0, s35
	s_nop 0
	global_load_lds_dwordx4 v[228:229], off
	s_waitcnt lgkmcnt(8)
	s_barrier
	s_waitcnt lgkmcnt(0)
	s_waitcnt lgkmcnt(0)
	v_mfma_f32_16x16x32_bf16 v[126:129], v[178:181], v[194:197], v[126:129]
	v_mfma_f32_16x16x32_bf16 v[122:125], v[186:189], v[194:197], v[122:125]
	v_mfma_f32_16x16x32_bf16 v[118:121], v[178:181], v[204:207], v[118:121]
	v_mfma_f32_16x16x32_bf16 v[114:117], v[186:189], v[204:207], v[114:117]
	v_mfma_f32_16x16x32_bf16 v[110:113], v[178:181], v[212:215], v[110:113]
	v_mfma_f32_16x16x32_bf16 v[106:109], v[186:189], v[212:215], v[106:109]
	v_mfma_f32_16x16x32_bf16 v[102:105], v[178:181], v[220:223], v[102:105]
	v_mfma_f32_16x16x32_bf16 v[98:101], v[186:189], v[220:223], v[98:101]
	v_mfma_f32_16x16x32_bf16 v[126:129], v[182:185], v[200:203], v[126:129]
	v_mfma_f32_16x16x32_bf16 v[122:125], v[190:193], v[200:203], v[122:125]
	v_mfma_f32_16x16x32_bf16 v[118:121], v[182:185], v[208:211], v[118:121]
	v_mfma_f32_16x16x32_bf16 v[114:117], v[190:193], v[208:211], v[114:117]
	v_mfma_f32_16x16x32_bf16 v[110:113], v[182:185], v[216:219], v[110:113]
	v_mfma_f32_16x16x32_bf16 v[106:109], v[190:193], v[216:219], v[106:109]
	v_mfma_f32_16x16x32_bf16 v[102:105], v[182:185], v[224:227], v[102:105]
	v_mfma_f32_16x16x32_bf16 v[98:101], v[190:193], v[224:227], v[98:101]
	s_barrier
	v_readfirstlane_b32 s35, v134
	v_lshl_add_u64 v[252:253], v[248:249], 0, s[24:25]
	s_mov_b32 m0, s35
	v_readfirstlane_b32 s35, v170
	ds_read_b128 v[228:231], v169
	ds_read_b128 v[232:235], v169 offset:1024
	ds_read_b128 v[236:239], v169 offset:2048
	ds_read_b128 v[240:243], v169 offset:3072
	global_load_lds_dwordx4 v[252:253], off
	v_lshl_add_u64 v[252:253], v[250:251], 0, s[24:25]
	s_mov_b32 m0, s35
	s_nop 0
	global_load_lds_dwordx4 v[252:253], off
	s_barrier
	s_waitcnt lgkmcnt(0)
	s_waitcnt lgkmcnt(0)
	v_mfma_f32_16x16x32_bf16 v[94:97], v[228:231], v[194:197], v[94:97]
	v_mfma_f32_16x16x32_bf16 v[90:93], v[236:239], v[194:197], v[90:93]
	v_mfma_f32_16x16x32_bf16 v[86:89], v[228:231], v[204:207], v[86:89]
	v_mfma_f32_16x16x32_bf16 v[82:85], v[236:239], v[204:207], v[82:85]
	v_mfma_f32_16x16x32_bf16 v[78:81], v[228:231], v[212:215], v[78:81]
	v_mfma_f32_16x16x32_bf16 v[74:77], v[236:239], v[212:215], v[74:77]
	v_mfma_f32_16x16x32_bf16 v[70:73], v[228:231], v[220:223], v[70:73]
	v_mfma_f32_16x16x32_bf16 v[66:69], v[236:239], v[220:223], v[66:69]
	v_mfma_f32_16x16x32_bf16 v[94:97], v[232:235], v[200:203], v[94:97]
	v_mfma_f32_16x16x32_bf16 v[90:93], v[240:243], v[200:203], v[90:93]
	v_mfma_f32_16x16x32_bf16 v[86:89], v[232:235], v[208:211], v[86:89]
	v_mfma_f32_16x16x32_bf16 v[82:85], v[240:243], v[208:211], v[82:85]
	v_mfma_f32_16x16x32_bf16 v[78:81], v[232:235], v[216:219], v[78:81]
	v_mfma_f32_16x16x32_bf16 v[74:77], v[240:243], v[216:219], v[74:77]
	v_mfma_f32_16x16x32_bf16 v[70:73], v[232:235], v[224:227], v[70:73]
	v_mfma_f32_16x16x32_bf16 v[66:69], v[240:243], v[224:227], v[66:69]
	v_readfirstlane_b32 s35, v171
	v_lshl_add_u64 v[244:245], v[244:245], 0, s[26:27]
	s_mov_b32 m0, s35
	v_readfirstlane_b32 s35, v172
	s_barrier
	ds_read_b128 v[194:197], v163 offset:49152
	ds_read_b128 v[200:203], v163 offset:50176
	ds_read_b128 v[204:207], v164 offset:49152
	ds_read_b128 v[208:211], v164 offset:50176
	ds_read_b128 v[212:215], v165 offset:49152
	ds_read_b128 v[216:219], v165 offset:50176
	ds_read_b128 v[220:223], v166 offset:49152
	ds_read_b128 v[224:227], v166 offset:50176
	global_load_lds_dwordx4 v[244:245], off
	v_lshl_add_u64 v[244:245], v[246:247], 0, s[26:27]
	s_mov_b32 m0, s35
	s_nop 0
	global_load_lds_dwordx4 v[244:245], off
	s_barrier
	s_waitcnt lgkmcnt(0)
	s_waitcnt lgkmcnt(0)
	v_mfma_f32_16x16x32_bf16 v[62:65], v[178:181], v[194:197], v[62:65]
	v_mfma_f32_16x16x32_bf16 v[58:61], v[186:189], v[194:197], v[58:61]
	v_mfma_f32_16x16x32_bf16 v[54:57], v[178:181], v[204:207], v[54:57]
	v_mfma_f32_16x16x32_bf16 v[50:53], v[186:189], v[204:207], v[50:53]
	v_mfma_f32_16x16x32_bf16 v[46:49], v[178:181], v[212:215], v[46:49]
	v_mfma_f32_16x16x32_bf16 v[42:45], v[186:189], v[212:215], v[42:45]
	v_mfma_f32_16x16x32_bf16 v[38:41], v[178:181], v[220:223], v[38:41]
	v_mfma_f32_16x16x32_bf16 v[34:37], v[186:189], v[220:223], v[34:37]
	v_mfma_f32_16x16x32_bf16 v[62:65], v[182:185], v[200:203], v[62:65]
	v_mfma_f32_16x16x32_bf16 v[58:61], v[190:193], v[200:203], v[58:61]
	v_mfma_f32_16x16x32_bf16 v[54:57], v[182:185], v[208:211], v[54:57]
	v_mfma_f32_16x16x32_bf16 v[50:53], v[190:193], v[208:211], v[50:53]
	v_mfma_f32_16x16x32_bf16 v[46:49], v[182:185], v[216:219], v[46:49]
	v_mfma_f32_16x16x32_bf16 v[42:45], v[190:193], v[216:219], v[42:45]
	v_mfma_f32_16x16x32_bf16 v[38:41], v[182:185], v[224:227], v[38:41]
	v_mfma_f32_16x16x32_bf16 v[34:37], v[190:193], v[224:227], v[34:37]
	s_barrier
	v_readfirstlane_b32 s35, v173
	v_lshl_add_u64 v[178:179], v[248:249], 0, s[28:29]
	s_mov_b32 m0, s35
	v_readfirstlane_b32 s35, v174
	global_load_lds_dwordx4 v[178:179], off
	v_lshl_add_u64 v[178:179], v[250:251], 0, s[28:29]
	s_mov_b32 m0, s35
	s_nop 0
	global_load_lds_dwordx4 v[178:179], off
	s_waitcnt vmcnt(6)
	s_barrier
	v_mfma_f32_16x16x32_bf16 v[30:33], v[228:231], v[194:197], v[30:33]
	v_mfma_f32_16x16x32_bf16 v[26:29], v[236:239], v[194:197], v[26:29]
	v_mfma_f32_16x16x32_bf16 v[22:25], v[228:231], v[204:207], v[22:25]
	v_mfma_f32_16x16x32_bf16 v[18:21], v[236:239], v[204:207], v[18:21]
	v_mfma_f32_16x16x32_bf16 v[14:17], v[228:231], v[212:215], v[14:17]
	v_mfma_f32_16x16x32_bf16 v[10:13], v[236:239], v[212:215], v[10:13]
	v_mfma_f32_16x16x32_bf16 v[6:9], v[228:231], v[220:223], v[6:9]
	v_mfma_f32_16x16x32_bf16 v[2:5], v[236:239], v[220:223], v[2:5]
	v_mfma_f32_16x16x32_bf16 v[30:33], v[232:235], v[200:203], v[30:33]
	v_mfma_f32_16x16x32_bf16 v[26:29], v[240:243], v[200:203], v[26:29]
	v_mfma_f32_16x16x32_bf16 v[22:25], v[232:235], v[208:211], v[22:25]
	v_mfma_f32_16x16x32_bf16 v[18:21], v[240:243], v[208:211], v[18:21]
	v_mfma_f32_16x16x32_bf16 v[14:17], v[232:235], v[216:219], v[14:17]
	v_mfma_f32_16x16x32_bf16 v[10:13], v[240:243], v[216:219], v[10:13]
	v_mfma_f32_16x16x32_bf16 v[6:9], v[232:235], v[224:227], v[6:9]
	v_mfma_f32_16x16x32_bf16 v[2:5], v[240:243], v[224:227], v[2:5]
	s_add_i32 s9, s9, 2
	s_add_u32 s36, s36, 0x100
	s_addc_u32 s37, s37, 0
	s_cmp_lt_u32 s9, 12
	s_barrier
	s_cbranch_scc1 .LBB0_2247
	v_readfirstlane_b32 s9, v175
	v_lshl_add_u64 v[140:141], v[140:141], 0, s[30:31]
	s_mov_b32 m0, s9
	v_readfirstlane_b32 s9, v176
	ds_read_b128 v[144:147], v162
	ds_read_b128 v[148:151], v162 offset:1024
	ds_read_b128 v[170:173], v162 offset:2048
	ds_read_b128 v[178:181], v162 offset:3072
	ds_read_b128 v[182:185], v163
	ds_read_b128 v[186:189], v163 offset:1024
	ds_read_b128 v[190:193], v164
	ds_read_b128 v[194:197], v164 offset:1024
	ds_read_b128 v[200:203], v165
	ds_read_b128 v[204:207], v165 offset:1024
	ds_read_b128 v[208:211], v166
	ds_read_b128 v[212:215], v166 offset:1024
	global_load_lds_dwordx4 v[140:141], off
	v_lshl_add_u64 v[140:141], v[142:143], 0, s[30:31]
	s_mov_b32 m0, s9
	s_nop 0
	global_load_lds_dwordx4 v[140:141], off
	s_barrier
	s_waitcnt lgkmcnt(0)
	s_waitcnt lgkmcnt(0)
	v_mfma_f32_16x16x32_bf16 v[126:129], v[144:147], v[182:185], v[126:129]
	v_mfma_f32_16x16x32_bf16 v[122:125], v[170:173], v[182:185], v[122:125]
	v_mfma_f32_16x16x32_bf16 v[114:117], v[170:173], v[190:193], v[114:117]
	v_mfma_f32_16x16x32_bf16 v[106:109], v[170:173], v[200:203], v[106:109]
	v_mfma_f32_16x16x32_bf16 v[98:101], v[170:173], v[208:211], v[98:101]
	v_mfma_f32_16x16x32_bf16 v[126:129], v[148:151], v[186:189], v[126:129]
	v_mfma_f32_16x16x32_bf16 v[122:125], v[178:181], v[186:189], v[122:125]
	v_mfma_f32_16x16x32_bf16 v[118:121], v[144:147], v[190:193], v[118:121]
	v_mfma_f32_16x16x32_bf16 v[114:117], v[178:181], v[194:197], v[114:117]
	v_mfma_f32_16x16x32_bf16 v[110:113], v[144:147], v[200:203], v[110:113]
	v_mfma_f32_16x16x32_bf16 v[106:109], v[178:181], v[204:207], v[106:109]
	v_mfma_f32_16x16x32_bf16 v[102:105], v[144:147], v[208:211], v[102:105]
	v_mfma_f32_16x16x32_bf16 v[98:101], v[178:181], v[212:215], v[98:101]
	v_mfma_f32_16x16x32_bf16 v[140:143], v[148:151], v[194:197], v[118:121]
	v_mfma_f32_16x16x32_bf16 v[174:177], v[148:151], v[204:207], v[110:113]
	v_mfma_f32_16x16x32_bf16 v[216:219], v[148:151], v[212:215], v[102:105]
	s_barrier
	s_nop 1
	ds_read_b128 v[102:105], v167
	ds_read_b128 v[110:113], v167 offset:1024
	ds_read_b128 v[118:121], v167 offset:2048
	ds_read_b128 v[220:223], v167 offset:3072
	s_barrier
	s_waitcnt lgkmcnt(0)
	s_waitcnt lgkmcnt(0)
	v_mfma_f32_16x16x32_bf16 v[90:93], v[118:121], v[182:185], v[90:93]
	v_mfma_f32_16x16x32_bf16 v[82:85], v[118:121], v[190:193], v[82:85]
	v_mfma_f32_16x16x32_bf16 v[74:77], v[118:121], v[200:203], v[74:77]
	v_mfma_f32_16x16x32_bf16 v[66:69], v[118:121], v[208:211], v[66:69]
	v_mfma_f32_16x16x32_bf16 v[94:97], v[102:105], v[182:185], v[94:97]
	v_mfma_f32_16x16x32_bf16 v[90:93], v[220:223], v[186:189], v[90:93]
	v_mfma_f32_16x16x32_bf16 v[86:89], v[102:105], v[190:193], v[86:89]
	v_mfma_f32_16x16x32_bf16 v[82:85], v[220:223], v[194:197], v[82:85]
	v_mfma_f32_16x16x32_bf16 v[78:81], v[102:105], v[200:203], v[78:81]
	v_mfma_f32_16x16x32_bf16 v[74:77], v[220:223], v[204:207], v[74:77]
	v_mfma_f32_16x16x32_bf16 v[70:73], v[102:105], v[208:211], v[70:73]
	v_mfma_f32_16x16x32_bf16 v[66:69], v[220:223], v[212:215], v[66:69]
	v_mfma_f32_16x16x32_bf16 v[224:227], v[110:113], v[186:189], v[94:97]
	v_mfma_f32_16x16x32_bf16 v[182:185], v[110:113], v[194:197], v[86:89]
	v_mfma_f32_16x16x32_bf16 v[186:189], v[110:113], v[204:207], v[78:81]
	v_mfma_f32_16x16x32_bf16 v[190:193], v[110:113], v[212:215], v[70:73]
	s_barrier
	s_nop 0
	ds_read_b128 v[70:73], v163 offset:16384
	ds_read_b128 v[78:81], v163 offset:17408
	ds_read_b128 v[86:89], v164 offset:16384
	ds_read_b128 v[94:97], v164 offset:17408
	ds_read_b128 v[194:197], v165 offset:16384
	ds_read_b128 v[200:203], v165 offset:17408
	ds_read_b128 v[204:207], v166 offset:16384
	ds_read_b128 v[208:211], v166 offset:17408
	s_waitcnt vmcnt(4)
	s_barrier
	s_waitcnt lgkmcnt(0)
	s_waitcnt lgkmcnt(0)
	v_mfma_f32_16x16x32_bf16 v[62:65], v[144:147], v[70:73], v[62:65]
	v_mfma_f32_16x16x32_bf16 v[58:61], v[170:173], v[70:73], v[58:61]
	v_mfma_f32_16x16x32_bf16 v[54:57], v[144:147], v[86:89], v[54:57]
	v_mfma_f32_16x16x32_bf16 v[50:53], v[170:173], v[86:89], v[50:53]
	v_mfma_f32_16x16x32_bf16 v[38:41], v[144:147], v[204:207], v[38:41]
	v_mfma_f32_16x16x32_bf16 v[34:37], v[170:173], v[204:207], v[34:37]
	v_mfma_f32_16x16x32_bf16 v[62:65], v[148:151], v[78:81], v[62:65]
	v_mfma_f32_16x16x32_bf16 v[58:61], v[178:181], v[78:81], v[58:61]
	v_mfma_f32_16x16x32_bf16 v[54:57], v[148:151], v[94:97], v[54:57]
	v_mfma_f32_16x16x32_bf16 v[50:53], v[178:181], v[94:97], v[50:53]
	v_mfma_f32_16x16x32_bf16 v[46:49], v[144:147], v[194:197], v[46:49]
	v_mfma_f32_16x16x32_bf16 v[42:45], v[170:173], v[194:197], v[42:45]
	v_mfma_f32_16x16x32_bf16 v[38:41], v[148:151], v[208:211], v[38:41]
	v_mfma_f32_16x16x32_bf16 v[34:37], v[178:181], v[208:211], v[34:37]
	v_mfma_f32_16x16x32_bf16 v[212:215], v[148:151], v[200:203], v[46:49]
	v_mfma_f32_16x16x32_bf16 v[228:231], v[178:181], v[200:203], v[42:45]
	v_mfma_f32_16x16x32_bf16 v[22:25], v[102:105], v[86:89], v[22:25]
	v_mfma_f32_16x16x32_bf16 v[18:21], v[118:121], v[86:89], v[18:21]
	v_mfma_f32_16x16x32_bf16 v[6:9], v[102:105], v[204:207], v[6:9]
	v_mfma_f32_16x16x32_bf16 v[2:5], v[118:121], v[204:207], v[2:5]
	v_mfma_f32_16x16x32_bf16 v[30:33], v[102:105], v[70:73], v[30:33]
	v_mfma_f32_16x16x32_bf16 v[26:29], v[118:121], v[70:73], v[26:29]
	v_mfma_f32_16x16x32_bf16 v[22:25], v[110:113], v[94:97], v[22:25]
	v_mfma_f32_16x16x32_bf16 v[18:21], v[220:223], v[94:97], v[18:21]
	v_mfma_f32_16x16x32_bf16 v[14:17], v[102:105], v[194:197], v[14:17]
	v_mfma_f32_16x16x32_bf16 v[10:13], v[118:121], v[194:197], v[10:13]
	v_mfma_f32_16x16x32_bf16 v[6:9], v[110:113], v[208:211], v[6:9]
	v_mfma_f32_16x16x32_bf16 v[2:5], v[220:223], v[208:211], v[2:5]
	v_mfma_f32_16x16x32_bf16 v[144:147], v[110:113], v[78:81], v[30:33]
	v_mfma_f32_16x16x32_bf16 v[148:151], v[220:223], v[78:81], v[26:29]
	v_mfma_f32_16x16x32_bf16 v[170:173], v[110:113], v[200:203], v[14:17]
	v_mfma_f32_16x16x32_bf16 v[178:181], v[220:223], v[200:203], v[10:13]
	s_barrier
	s_nop 0
	ds_read_b128 v[10:13], v168
	ds_read_b128 v[14:17], v168 offset:1024
	ds_read_b128 v[194:197], v168 offset:2048
	ds_read_b128 v[200:203], v168 offset:3072
	ds_read_b128 v[26:29], v163 offset:32768
	ds_read_b128 v[30:33], v163 offset:33792
	ds_read_b128 v[42:45], v164 offset:32768
	ds_read_b128 v[46:49], v164 offset:33792
	ds_read_b128 v[204:207], v165 offset:32768
	ds_read_b128 v[208:211], v165 offset:33792
	ds_read_b128 v[220:223], v166 offset:32768
	ds_read_b128 v[232:235], v166 offset:33792
	s_waitcnt vmcnt(2)
	s_barrier
	s_waitcnt lgkmcnt(0)
	s_waitcnt lgkmcnt(0)
	v_mfma_f32_16x16x32_bf16 v[70:73], v[10:13], v[26:29], v[126:129]
	v_mfma_f32_16x16x32_bf16 v[126:129], v[14:17], v[30:33], v[70:73]
	v_mfma_f32_16x16x32_bf16 v[70:73], v[194:197], v[26:29], v[122:125]
	v_mfma_f32_16x16x32_bf16 v[118:121], v[200:203], v[30:33], v[70:73]
	v_mfma_f32_16x16x32_bf16 v[70:73], v[10:13], v[42:45], v[140:143]
	v_mfma_f32_16x16x32_bf16 v[110:113], v[14:17], v[46:49], v[70:73]
	v_mfma_f32_16x16x32_bf16 v[70:73], v[194:197], v[42:45], v[114:117]
	v_mfma_f32_16x16x32_bf16 v[102:105], v[200:203], v[46:49], v[70:73]
	v_mfma_f32_16x16x32_bf16 v[70:73], v[10:13], v[204:207], v[174:177]
	v_mfma_f32_16x16x32_bf16 v[94:97], v[14:17], v[208:211], v[70:73]
	v_mfma_f32_16x16x32_bf16 v[70:73], v[194:197], v[204:207], v[106:109]
	v_mfma_f32_16x16x32_bf16 v[86:89], v[200:203], v[208:211], v[70:73]
	v_mfma_f32_16x16x32_bf16 v[70:73], v[10:13], v[220:223], v[216:219]
	v_mfma_f32_16x16x32_bf16 v[78:81], v[14:17], v[232:235], v[70:73]
	v_mfma_f32_16x16x32_bf16 v[70:73], v[194:197], v[220:223], v[98:101]
	v_mfma_f32_16x16x32_bf16 v[70:73], v[200:203], v[232:235], v[70:73]
	s_barrier
	ds_read_b128 v[140:143], v169
	ds_read_b128 v[174:177], v169 offset:1024
	ds_read_b128 v[216:219], v169 offset:2048
	ds_read_b128 v[236:239], v169 offset:3072
	s_waitcnt vmcnt(0)
	s_barrier
	s_waitcnt lgkmcnt(0)
	s_waitcnt lgkmcnt(0)
	v_mfma_f32_16x16x32_bf16 v[98:101], v[140:143], v[26:29], v[224:227]
	v_mfma_f32_16x16x32_bf16 v[26:29], v[216:219], v[26:29], v[90:93]
	v_mfma_f32_16x16x32_bf16 v[114:117], v[236:239], v[30:33], v[26:29]
	v_mfma_f32_16x16x32_bf16 v[26:29], v[140:143], v[42:45], v[182:185]
	v_mfma_f32_16x16x32_bf16 v[106:109], v[174:177], v[46:49], v[26:29]
	v_mfma_f32_16x16x32_bf16 v[26:29], v[216:219], v[42:45], v[82:85]
	v_mfma_f32_16x16x32_bf16 v[122:125], v[174:177], v[30:33], v[98:101]
	v_mfma_f32_16x16x32_bf16 v[98:101], v[236:239], v[46:49], v[26:29]
	v_mfma_f32_16x16x32_bf16 v[26:29], v[140:143], v[204:207], v[186:189]
	v_mfma_f32_16x16x32_bf16 v[90:93], v[174:177], v[208:211], v[26:29]
	v_mfma_f32_16x16x32_bf16 v[26:29], v[216:219], v[204:207], v[74:77]
	v_mfma_f32_16x16x32_bf16 v[82:85], v[236:239], v[208:211], v[26:29]
	v_mfma_f32_16x16x32_bf16 v[26:29], v[140:143], v[220:223], v[190:193]
	v_mfma_f32_16x16x32_bf16 v[74:77], v[174:177], v[232:235], v[26:29]
	v_mfma_f32_16x16x32_bf16 v[26:29], v[216:219], v[220:223], v[66:69]
	v_mfma_f32_16x16x32_bf16 v[66:69], v[236:239], v[232:235], v[26:29]
	s_barrier
	ds_read_b128 v[182:185], v163 offset:49152
	ds_read_b128 v[186:189], v163 offset:50176
	ds_read_b128 v[190:193], v164 offset:49152
	ds_read_b128 v[204:207], v164 offset:50176
	ds_read_b128 v[208:211], v165 offset:49152
	ds_read_b128 v[220:223], v165 offset:50176
	ds_read_b128 v[224:227], v166 offset:49152
	ds_read_b128 v[232:235], v166 offset:50176
	s_barrier
	s_waitcnt lgkmcnt(0)
	s_waitcnt lgkmcnt(0)
	v_mfma_f32_16x16x32_bf16 v[26:29], v[10:13], v[182:185], v[62:65]
	v_mfma_f32_16x16x32_bf16 v[62:65], v[14:17], v[186:189], v[26:29]
	v_mfma_f32_16x16x32_bf16 v[26:29], v[194:197], v[182:185], v[58:61]
	v_mfma_f32_16x16x32_bf16 v[58:61], v[200:203], v[186:189], v[26:29]
	v_mfma_f32_16x16x32_bf16 v[26:29], v[10:13], v[190:193], v[54:57]
	v_mfma_f32_16x16x32_bf16 v[46:49], v[14:17], v[204:207], v[26:29]
	v_mfma_f32_16x16x32_bf16 v[26:29], v[194:197], v[190:193], v[50:53]
	v_mfma_f32_16x16x32_bf16 v[42:45], v[200:203], v[204:207], v[26:29]
	v_mfma_f32_16x16x32_bf16 v[26:29], v[10:13], v[208:211], v[212:215]
	v_mfma_f32_16x16x32_bf16 v[10:13], v[10:13], v[224:227], v[38:41]
	v_mfma_f32_16x16x32_bf16 v[30:33], v[14:17], v[220:223], v[26:29]
	v_mfma_f32_16x16x32_bf16 v[26:29], v[194:197], v[208:211], v[228:231]
	v_mfma_f32_16x16x32_bf16 v[14:17], v[14:17], v[232:235], v[10:13]
	v_mfma_f32_16x16x32_bf16 v[10:13], v[194:197], v[224:227], v[34:37]
	v_mfma_f32_16x16x32_bf16 v[26:29], v[200:203], v[220:223], v[26:29]
	v_mfma_f32_16x16x32_bf16 v[10:13], v[200:203], v[232:235], v[10:13]
	v_mfma_f32_16x16x32_bf16 v[34:37], v[140:143], v[182:185], v[144:147]
	v_mfma_f32_16x16x32_bf16 v[54:57], v[174:177], v[186:189], v[34:37]
	v_mfma_f32_16x16x32_bf16 v[34:37], v[216:219], v[182:185], v[148:151]
	v_mfma_f32_16x16x32_bf16 v[18:21], v[216:219], v[190:193], v[18:21]
	v_mfma_f32_16x16x32_bf16 v[50:53], v[236:239], v[186:189], v[34:37]
	v_mfma_f32_16x16x32_bf16 v[22:25], v[140:143], v[190:193], v[22:25]
	v_mfma_f32_16x16x32_bf16 v[34:37], v[236:239], v[204:207], v[18:21]
	v_mfma_f32_16x16x32_bf16 v[18:21], v[140:143], v[208:211], v[170:173]
	v_mfma_f32_16x16x32_bf16 v[38:41], v[174:177], v[204:207], v[22:25]
	v_mfma_f32_16x16x32_bf16 v[22:25], v[174:177], v[220:223], v[18:21]
	v_mfma_f32_16x16x32_bf16 v[18:21], v[216:219], v[208:211], v[178:181]
	v_mfma_f32_16x16x32_bf16 v[6:9], v[140:143], v[224:227], v[6:9]
	v_mfma_f32_16x16x32_bf16 v[2:5], v[216:219], v[224:227], v[2:5]
	v_mfma_f32_16x16x32_bf16 v[18:21], v[236:239], v[220:223], v[18:21]
	v_mfma_f32_16x16x32_bf16 v[6:9], v[174:177], v[232:235], v[6:9]
	v_mfma_f32_16x16x32_bf16 v[2:5], v[236:239], v[232:235], v[2:5]
	s_barrier
	s_and_saveexec_b64 s[36:37], s[6:7]
	v_readlane_b32 s64, v254, 29
	v_readlane_b32 s65, v254, 30
	v_readlane_b32 s66, v254, 31
	v_readlane_b32 s67, v254, 32
	v_readlane_b32 s68, v254, 33
	v_readlane_b32 s69, v254, 34
	v_readlane_b32 s70, v254, 35
	v_readlane_b32 s71, v254, 36
	v_readlane_b32 s72, v254, 37
	v_readlane_b32 s73, v254, 38
	v_readlane_b32 s74, v254, 39
	v_readlane_b32 s75, v254, 40
	v_readlane_b32 s76, v254, 41
	v_readlane_b32 s77, v254, 42
	v_readlane_b32 s78, v254, 43
	v_readlane_b32 s79, v254, 44
	s_cbranch_execz .LBB0_2250
	s_barrier
.LBB0_2250:
	s_setprio 0
	s_or_b64 exec, exec, s[36:37]
	v_mov_b32_e32 v140, v0
	s_nop 0
	v_ashrrev_i32_e32 v134, 2, v140
	v_and_b32_e32 v134, 0xffffffc0, v134
	v_add_u32_e32 v134, s34, v134
	v_and_or_b32 v142, v140, 15, v134
	v_cmp_lt_i32_e32 vcc, s62, v142
	s_and_saveexec_b64 s[34:35], vcc
	s_xor_b64 s[34:35], exec, s[34:35]
	v_add_u32_e32 v134, 0xffffc000, v142
	v_lshlrev_b64 v[144:145], 12, v[134:135]
	v_lshl_add_u64 v[144:145], s[66:67], 0, v[144:145]
	v_mov_b32_e32 v143, v135
	s_andn2_saveexec_b64 s[34:35], s[34:35]
	v_ashrrev_i32_e32 v143, 31, v142
	v_lshlrev_b64 v[144:145], 12, v[142:143]
	v_lshl_add_u64 v[144:145], s[64:65], 0, v[144:145]
	s_or_b64 exec, exec, s[34:35]
	v_bfe_u32 v134, v140, 4, 2
	v_lshrrev_b32_e32 v140, 1, v140
	v_and_b32_e32 v140, 0x60, v140
	v_lshlrev_b32_e32 v141, 2, v134
	v_or3_b32 v140, v141, v140, s8
	v_ashrrev_i32_e32 v141, 31, v140
	v_lshl_add_u64 v[148:149], v[140:141], 2, v[144:145]
	global_load_dwordx4 v[144:147], v[148:149], off
	v_lshlrev_b64 v[150:151], 11, v[142:143]
	v_lshl_add_u64 v[150:151], s[94:95], 0, v[150:151]
	v_lshl_add_u64 v[150:151], v[140:141], 1, v[150:151]
	s_waitcnt vmcnt(0)
	v_pk_add_f32 v[146:147], v[128:129], v[146:147]
	v_pk_add_f32 v[144:145], v[126:127], v[144:145]
	v_cvt_pk_bf16_f32 v127, v146, v147
	s_nop 0
	v_cvt_pk_bf16_f32 v126, v144, v145
	global_store_dwordx2 v[150:151], v[126:127], off
	global_load_dwordx4 v[126:129], v[148:149], off offset:64
	v_mul_f32_e32 v145, v145, v145
	v_fmac_f32_e32 v145, v144, v144
	v_fmac_f32_e32 v145, v146, v146
	v_fmac_f32_e32 v145, v147, v147
	s_waitcnt vmcnt(0)
	v_pk_add_f32 v[128:129], v[120:121], v[128:129]
	v_pk_add_f32 v[126:127], v[118:119], v[126:127]
	v_cvt_pk_bf16_f32 v119, v128, v129
	s_nop 0
	v_cvt_pk_bf16_f32 v118, v126, v127
	global_store_dwordx2 v[150:151], v[118:119], off offset:32
	global_load_dwordx4 v[118:121], v[148:149], off offset:512
	v_mul_f32_e32 v127, v127, v127
	v_fmac_f32_e32 v127, v126, v126
	v_fmac_f32_e32 v127, v128, v128
	v_fmac_f32_e32 v127, v129, v129
	v_add_f32_e32 v126, v145, v127
	s_waitcnt vmcnt(0)
	v_pk_add_f32 v[124:125], v[124:125], v[120:121]
	v_pk_add_f32 v[170:171], v[122:123], v[118:119]
	v_cvt_pk_bf16_f32 v119, v124, v125
	s_nop 0
	v_cvt_pk_bf16_f32 v118, v170, v171
	global_store_dwordx2 v[150:151], v[118:119], off offset:256
	global_load_dwordx4 v[120:123], v[148:149], off offset:576
	v_mul_f32_e32 v127, v171, v171
	v_and_b32_e32 v119, 64, v161
	v_fmac_f32_e32 v127, v170, v170
	v_xor_b32_e32 v118, 16, v161
	v_add_u32_e32 v119, 64, v119
	v_fmac_f32_e32 v127, v124, v124
	v_cmp_lt_i32_e32 vcc, v118, v119
	v_fmac_f32_e32 v127, v125, v125
	v_add_f32_e32 v124, v126, v127
	v_cndmask_b32_e32 v118, v161, v118, vcc
	v_lshlrev_b32_e32 v118, 2, v118
	s_waitcnt vmcnt(0)
	v_pk_add_f32 v[120:121], v[114:115], v[120:121]
	s_nop 0
	v_mul_f32_e32 v114, v121, v121
	v_pk_add_f32 v[116:117], v[116:117], v[122:123]
	v_fmac_f32_e32 v114, v120, v120
	v_fmac_f32_e32 v114, v116, v116
	v_fmac_f32_e32 v114, v117, v117
	v_add_f32_e32 v114, v124, v114
	ds_bpermute_b32 v115, v118, v114
	v_xor_b32_e32 v122, 32, v161
	v_cmp_lt_i32_e32 vcc, v122, v119
	v_cvt_pk_bf16_f32 v120, v120, v121
	v_cvt_pk_bf16_f32 v121, v116, v117
	s_waitcnt lgkmcnt(0)
	v_add_f32_e32 v114, v114, v115
	global_store_dwordx2 v[150:151], v[120:121], off offset:288
	v_cndmask_b32_e32 v119, v161, v122, vcc
	v_lshlrev_b32_e32 v119, 2, v119
	ds_bpermute_b32 v115, v119, v114
	v_cmp_eq_u32_e32 vcc, 0, v134
	s_and_saveexec_b64 s[8:9], vcc
	s_cbranch_execz .LBB0_2256
	s_waitcnt lgkmcnt(0)
	v_add_f32_e32 v116, v114, v115
	v_lshl_add_u64 v[114:115], v[142:143], 2, s[12:13]
	global_atomic_add_f32 v[114:115], v116, off

.LBB0_2577:
	s_or_b64 exec, exec, s[6:7]
	s_bfe_i32 s6, s81, 0x80000
	s_sext_i32_i16 s6, s6
	s_lshr_b32 s46, s6, 3
	s_sext_i32_i8 s47, s46
	s_mul_i32 s36, s47, 0x160000
	s_ashr_i32 s37, s36, 31
	s_add_u32 s42, s12, s36
	v_add_u32_e32 v134, s65, v166
	s_addc_u32 s43, s13, s37
	v_readfirstlane_b32 s6, v134
	v_add_u32_e32 v148, 0x2000, v134
	v_lshl_add_u64 v[2:3], s[42:43], 0, v[132:133]
	s_mov_b32 m0, s6
	v_readfirstlane_b32 s6, v148
	s_mul_i32 s38, s35, 0x1600
	s_waitcnt vmcnt(0)
	s_barrier
	global_load_lds_dwordx4 v[2:3], off
	s_mov_b32 m0, s6
	s_mul_hi_i32 s39, s35, 0x1600
	s_add_u32 s6, s4, s38
	v_add_u32_e32 v149, 16, v166
	v_lshl_add_u64 v[4:5], s[42:43], 0, v[130:131]
	s_addc_u32 s7, s5, s39
	v_readfirstlane_b32 s44, v149
	v_add_u32_e32 v150, 0x2000, v149
	global_load_lds_dwordx4 v[4:5], off
	v_lshl_add_u64 v[6:7], s[6:7], 0, v[132:133]
	s_mov_b32 m0, s44
	v_lshl_add_u64 v[8:9], s[6:7], 0, v[130:131]
	v_readfirstlane_b32 s6, v150
	global_load_lds_dwordx4 v[6:7], off
	s_mov_b32 m0, s6
	s_add_u32 s6, s42, 0xb0000
	v_add_u32_e32 v151, s66, v166
	s_addc_u32 s7, s43, 0
	v_readfirstlane_b32 s44, v151
	global_load_lds_dwordx4 v[8:9], off
	v_lshl_add_u64 v[10:11], s[6:7], 0, v[132:133]
	s_mov_b32 m0, s44
	v_add_u32_e32 v152, 0x2000, v151
	global_load_lds_dwordx4 v[10:11], off
	v_lshl_add_u64 v[10:11], s[6:7], 0, v[130:131]
	v_readfirstlane_b32 s6, v152
	s_mov_b32 m0, s6
	s_or_b32 s6, s35, 0x80
	s_mul_hi_i32 s7, s6, 0x1600
	s_mulk_i32 s6, 0x1600
	s_add_u32 s6, s4, s6
	v_add_u32_e32 v153, 0x4000, v149
	s_addc_u32 s7, s5, s7
	v_readfirstlane_b32 s44, v153
	v_add_u32_e32 v154, 0x6000, v149
	global_load_lds_dwordx4 v[10:11], off
	v_lshl_add_u64 v[10:11], s[6:7], 0, v[132:133]
	s_mov_b32 m0, s44
	v_readfirstlane_b32 s44, v154
	global_load_lds_dwordx4 v[10:11], off
	v_lshl_add_u64 v[10:11], s[6:7], 0, v[130:131]
	s_mov_b32 m0, s44
	s_nop 0
	global_load_lds_dwordx4 v[10:11], off
	s_and_saveexec_b64 s[44:45], s[0:1]
	s_cbranch_execz .LBB0_2579
	s_barrier
	s_setprio 1

.LBB0_2580:
	ds_read_b128 v[176:179], v168
	ds_read_b128 v[180:183], v168 offset:1024
	ds_read_b128 v[184:187], v168 offset:2048
	ds_read_b128 v[188:191], v168 offset:3072
	v_add_u32_e32 v161, 0xc000, v149
	v_lshl_add_u64 v[164:165], s[36:37], 0, v[144:145]
	v_readfirstlane_b32 s39, v161
	v_lshl_add_u64 v[162:163], v[164:165], 0, s[16:17]
	s_mov_b32 m0, s39
	ds_read_b128 v[192:195], v169
	ds_read_b128 v[200:203], v169 offset:1024
	ds_read_b128 v[204:207], v170
	ds_read_b128 v[208:211], v170 offset:1024
	ds_read_b128 v[212:215], v171
	ds_read_b128 v[216:219], v171 offset:1024
	ds_read_b128 v[220:223], v172
	ds_read_b128 v[224:227], v172 offset:1024
	global_load_lds_dwordx4 v[162:163], off
	v_add_u32_e32 v162, 0xe000, v149
	v_lshl_add_u64 v[196:197], s[36:37], 0, v[146:147]
	v_readfirstlane_b32 s39, v162
	v_lshl_add_u64 v[228:229], v[196:197], 0, s[16:17]
	s_mov_b32 m0, s39
	s_nop 0
	global_load_lds_dwordx4 v[228:229], off
	s_waitcnt lgkmcnt(8)
	s_barrier
	s_waitcnt lgkmcnt(0)
	s_waitcnt lgkmcnt(0)
	v_mfma_f32_16x16x32_bf16 v[126:129], v[176:179], v[192:195], v[126:129]
	v_mfma_f32_16x16x32_bf16 v[122:125], v[184:187], v[192:195], v[122:125]
	v_mfma_f32_16x16x32_bf16 v[118:121], v[176:179], v[204:207], v[118:121]
	v_mfma_f32_16x16x32_bf16 v[114:117], v[184:187], v[204:207], v[114:117]
	v_mfma_f32_16x16x32_bf16 v[110:113], v[176:179], v[212:215], v[110:113]
	v_mfma_f32_16x16x32_bf16 v[106:109], v[184:187], v[212:215], v[106:109]
	v_mfma_f32_16x16x32_bf16 v[102:105], v[176:179], v[220:223], v[102:105]
	v_mfma_f32_16x16x32_bf16 v[98:101], v[184:187], v[220:223], v[98:101]
	v_mfma_f32_16x16x32_bf16 v[126:129], v[180:183], v[200:203], v[126:129]
	v_mfma_f32_16x16x32_bf16 v[122:125], v[188:191], v[200:203], v[122:125]
	v_mfma_f32_16x16x32_bf16 v[118:121], v[180:183], v[208:211], v[118:121]
	v_mfma_f32_16x16x32_bf16 v[114:117], v[188:191], v[208:211], v[114:117]
	v_mfma_f32_16x16x32_bf16 v[110:113], v[180:183], v[216:219], v[110:113]
	v_mfma_f32_16x16x32_bf16 v[106:109], v[188:191], v[216:219], v[106:109]
	v_mfma_f32_16x16x32_bf16 v[102:105], v[180:183], v[224:227], v[102:105]
	v_mfma_f32_16x16x32_bf16 v[98:101], v[188:191], v[224:227], v[98:101]
	s_barrier
	v_lshl_add_u64 v[244:245], s[36:37], 0, v[140:141]
	v_readfirstlane_b32 s39, v134
	v_lshl_add_u64 v[246:247], v[244:245], 0, s[18:19]
	s_mov_b32 m0, s39
	ds_read_b128 v[228:231], v173
	ds_read_b128 v[232:235], v173 offset:1024
	ds_read_b128 v[236:239], v173 offset:2048
	ds_read_b128 v[240:243], v173 offset:3072
	global_load_lds_dwordx4 v[246:247], off
	v_lshl_add_u64 v[246:247], s[36:37], 0, v[142:143]
	v_readfirstlane_b32 s39, v148
	v_lshl_add_u64 v[248:249], v[246:247], 0, s[18:19]
	s_mov_b32 m0, s39
	s_nop 0
	global_load_lds_dwordx4 v[248:249], off
	s_barrier
	s_waitcnt lgkmcnt(0)
	s_waitcnt lgkmcnt(0)
	v_mfma_f32_16x16x32_bf16 v[94:97], v[228:231], v[192:195], v[94:97]
	v_mfma_f32_16x16x32_bf16 v[90:93], v[236:239], v[192:195], v[90:93]
	v_mfma_f32_16x16x32_bf16 v[86:89], v[228:231], v[204:207], v[86:89]
	v_mfma_f32_16x16x32_bf16 v[82:85], v[236:239], v[204:207], v[82:85]
	v_mfma_f32_16x16x32_bf16 v[78:81], v[228:231], v[212:215], v[78:81]
	v_mfma_f32_16x16x32_bf16 v[74:77], v[236:239], v[212:215], v[74:77]
	v_mfma_f32_16x16x32_bf16 v[70:73], v[228:231], v[220:223], v[70:73]
	v_mfma_f32_16x16x32_bf16 v[66:69], v[236:239], v[220:223], v[66:69]
	v_mfma_f32_16x16x32_bf16 v[94:97], v[232:235], v[200:203], v[94:97]
	v_mfma_f32_16x16x32_bf16 v[90:93], v[240:243], v[200:203], v[90:93]
	v_mfma_f32_16x16x32_bf16 v[86:89], v[232:235], v[208:211], v[86:89]
	v_mfma_f32_16x16x32_bf16 v[82:85], v[240:243], v[208:211], v[82:85]
	v_mfma_f32_16x16x32_bf16 v[78:81], v[232:235], v[216:219], v[78:81]
	v_mfma_f32_16x16x32_bf16 v[74:77], v[240:243], v[216:219], v[74:77]
	v_mfma_f32_16x16x32_bf16 v[70:73], v[232:235], v[224:227], v[70:73]
	v_mfma_f32_16x16x32_bf16 v[66:69], v[240:243], v[224:227], v[66:69]
	v_readfirstlane_b32 s39, v149
	v_lshl_add_u64 v[248:249], v[164:165], 0, s[20:21]
	s_mov_b32 m0, s39
	v_readfirstlane_b32 s39, v150
	s_barrier
	ds_read_b128 v[192:195], v169 offset:16384
	ds_read_b128 v[200:203], v169 offset:17408
	ds_read_b128 v[204:207], v170 offset:16384
	ds_read_b128 v[208:211], v170 offset:17408
	ds_read_b128 v[212:215], v171 offset:16384
	ds_read_b128 v[216:219], v171 offset:17408
	ds_read_b128 v[220:223], v172 offset:16384
	ds_read_b128 v[224:227], v172 offset:17408
	global_load_lds_dwordx4 v[248:249], off
	v_lshl_add_u64 v[248:249], v[196:197], 0, s[20:21]
	s_mov_b32 m0, s39
	s_nop 0
	global_load_lds_dwordx4 v[248:249], off
	s_barrier
	s_waitcnt lgkmcnt(0)
	s_waitcnt lgkmcnt(0)
	v_mfma_f32_16x16x32_bf16 v[62:65], v[176:179], v[192:195], v[62:65]
	v_mfma_f32_16x16x32_bf16 v[58:61], v[184:187], v[192:195], v[58:61]
	v_mfma_f32_16x16x32_bf16 v[54:57], v[176:179], v[204:207], v[54:57]
	v_mfma_f32_16x16x32_bf16 v[50:53], v[184:187], v[204:207], v[50:53]
	v_mfma_f32_16x16x32_bf16 v[46:49], v[176:179], v[212:215], v[46:49]
	v_mfma_f32_16x16x32_bf16 v[42:45], v[184:187], v[212:215], v[42:45]
	v_mfma_f32_16x16x32_bf16 v[38:41], v[176:179], v[220:223], v[38:41]
	v_mfma_f32_16x16x32_bf16 v[34:37], v[184:187], v[220:223], v[34:37]
	v_mfma_f32_16x16x32_bf16 v[62:65], v[180:183], v[200:203], v[62:65]
	v_mfma_f32_16x16x32_bf16 v[58:61], v[188:191], v[200:203], v[58:61]
	v_mfma_f32_16x16x32_bf16 v[54:57], v[180:183], v[208:211], v[54:57]
	v_mfma_f32_16x16x32_bf16 v[50:53], v[188:191], v[208:211], v[50:53]
	v_mfma_f32_16x16x32_bf16 v[46:49], v[180:183], v[216:219], v[46:49]
	v_mfma_f32_16x16x32_bf16 v[42:45], v[188:191], v[216:219], v[42:45]
	v_mfma_f32_16x16x32_bf16 v[38:41], v[180:183], v[224:227], v[38:41]
	v_mfma_f32_16x16x32_bf16 v[34:37], v[188:191], v[224:227], v[34:37]
	s_barrier
	v_readfirstlane_b32 s39, v151
	v_lshl_add_u64 v[176:177], v[244:245], 0, s[22:23]
	s_mov_b32 m0, s39
	v_readfirstlane_b32 s39, v152
	global_load_lds_dwordx4 v[176:177], off
	v_lshl_add_u64 v[176:177], v[246:247], 0, s[22:23]
	s_mov_b32 m0, s39
	s_nop 0
	global_load_lds_dwordx4 v[176:177], off
	s_waitcnt vmcnt(6)
	s_barrier
	v_mfma_f32_16x16x32_bf16 v[30:33], v[228:231], v[192:195], v[30:33]
	v_mfma_f32_16x16x32_bf16 v[26:29], v[236:239], v[192:195], v[26:29]
	v_mfma_f32_16x16x32_bf16 v[22:25], v[228:231], v[204:207], v[22:25]
	v_mfma_f32_16x16x32_bf16 v[18:21], v[236:239], v[204:207], v[18:21]
	v_mfma_f32_16x16x32_bf16 v[14:17], v[228:231], v[212:215], v[14:17]
	v_mfma_f32_16x16x32_bf16 v[10:13], v[236:239], v[212:215], v[10:13]
	v_mfma_f32_16x16x32_bf16 v[6:9], v[228:231], v[220:223], v[6:9]
	v_mfma_f32_16x16x32_bf16 v[2:5], v[236:239], v[220:223], v[2:5]
	v_mfma_f32_16x16x32_bf16 v[30:33], v[232:235], v[200:203], v[30:33]
	v_mfma_f32_16x16x32_bf16 v[26:29], v[240:243], v[200:203], v[26:29]
	v_mfma_f32_16x16x32_bf16 v[22:25], v[232:235], v[208:211], v[22:25]
	v_mfma_f32_16x16x32_bf16 v[18:21], v[240:243], v[208:211], v[18:21]
	v_mfma_f32_16x16x32_bf16 v[14:17], v[232:235], v[216:219], v[14:17]
	v_mfma_f32_16x16x32_bf16 v[10:13], v[240:243], v[216:219], v[10:13]
	v_mfma_f32_16x16x32_bf16 v[6:9], v[232:235], v[224:227], v[6:9]
	v_mfma_f32_16x16x32_bf16 v[2:5], v[240:243], v[224:227], v[2:5]
	s_barrier
	ds_read_b128 v[176:179], v174
	ds_read_b128 v[180:183], v174 offset:1024
	ds_read_b128 v[184:187], v174 offset:2048
	ds_read_b128 v[188:191], v174 offset:3072
	v_readfirstlane_b32 s39, v153
	v_lshl_add_u64 v[228:229], v[164:165], 0, s[24:25]
	s_mov_b32 m0, s39
	v_readfirstlane_b32 s39, v154
	ds_read_b128 v[192:195], v169 offset:32768
	ds_read_b128 v[200:203], v169 offset:33792
	ds_read_b128 v[204:207], v170 offset:32768
	ds_read_b128 v[208:211], v170 offset:33792
	ds_read_b128 v[212:215], v171 offset:32768
	ds_read_b128 v[216:219], v171 offset:33792
	ds_read_b128 v[220:223], v172 offset:32768
	ds_read_b128 v[224:227], v172 offset:33792
	global_load_lds_dwordx4 v[228:229], off
	v_lshl_add_u64 v[228:229], v[196:197], 0, s[24:25]
	s_mov_b32 m0, s39
	s_nop 0
	global_load_lds_dwordx4 v[228:229], off
	s_waitcnt lgkmcnt(8)
	s_barrier
	s_waitcnt lgkmcnt(0)
	s_waitcnt lgkmcnt(0)
	v_mfma_f32_16x16x32_bf16 v[126:129], v[176:179], v[192:195], v[126:129]
	v_mfma_f32_16x16x32_bf16 v[122:125], v[184:187], v[192:195], v[122:125]
	v_mfma_f32_16x16x32_bf16 v[118:121], v[176:179], v[204:207], v[118:121]
	v_mfma_f32_16x16x32_bf16 v[114:117], v[184:187], v[204:207], v[114:117]
	v_mfma_f32_16x16x32_bf16 v[110:113], v[176:179], v[212:215], v[110:113]
	v_mfma_f32_16x16x32_bf16 v[106:109], v[184:187], v[212:215], v[106:109]
	v_mfma_f32_16x16x32_bf16 v[102:105], v[176:179], v[220:223], v[102:105]
	v_mfma_f32_16x16x32_bf16 v[98:101], v[184:187], v[220:223], v[98:101]
	v_mfma_f32_16x16x32_bf16 v[126:129], v[180:183], v[200:203], v[126:129]
	v_mfma_f32_16x16x32_bf16 v[122:125], v[188:191], v[200:203], v[122:125]
	v_mfma_f32_16x16x32_bf16 v[118:121], v[180:183], v[208:211], v[118:121]
	v_mfma_f32_16x16x32_bf16 v[114:117], v[188:191], v[208:211], v[114:117]
	v_mfma_f32_16x16x32_bf16 v[110:113], v[180:183], v[216:219], v[110:113]
	v_mfma_f32_16x16x32_bf16 v[106:109], v[188:191], v[216:219], v[106:109]
	v_mfma_f32_16x16x32_bf16 v[102:105], v[180:183], v[224:227], v[102:105]
	v_mfma_f32_16x16x32_bf16 v[98:101], v[188:191], v[224:227], v[98:101]
	s_barrier
	v_readfirstlane_b32 s39, v155
	v_lshl_add_u64 v[248:249], v[244:245], 0, s[26:27]
	s_mov_b32 m0, s39
	v_readfirstlane_b32 s39, v156
	ds_read_b128 v[228:231], v175
	ds_read_b128 v[232:235], v175 offset:1024
	ds_read_b128 v[236:239], v175 offset:2048
	ds_read_b128 v[240:243], v175 offset:3072
	global_load_lds_dwordx4 v[248:249], off
	v_lshl_add_u64 v[248:249], v[246:247], 0, s[26:27]
	s_mov_b32 m0, s39
	s_nop 0
	global_load_lds_dwordx4 v[248:249], off
	s_barrier
	s_waitcnt lgkmcnt(0)
	s_waitcnt lgkmcnt(0)
	v_mfma_f32_16x16x32_bf16 v[94:97], v[228:231], v[192:195], v[94:97]
	v_mfma_f32_16x16x32_bf16 v[90:93], v[236:239], v[192:195], v[90:93]
	v_mfma_f32_16x16x32_bf16 v[86:89], v[228:231], v[204:207], v[86:89]
	v_mfma_f32_16x16x32_bf16 v[82:85], v[236:239], v[204:207], v[82:85]
	v_mfma_f32_16x16x32_bf16 v[78:81], v[228:231], v[212:215], v[78:81]
	v_mfma_f32_16x16x32_bf16 v[74:77], v[236:239], v[212:215], v[74:77]
	v_mfma_f32_16x16x32_bf16 v[70:73], v[228:231], v[220:223], v[70:73]
	v_mfma_f32_16x16x32_bf16 v[66:69], v[236:239], v[220:223], v[66:69]
	v_mfma_f32_16x16x32_bf16 v[94:97], v[232:235], v[200:203], v[94:97]
	v_mfma_f32_16x16x32_bf16 v[90:93], v[240:243], v[200:203], v[90:93]
	v_mfma_f32_16x16x32_bf16 v[86:89], v[232:235], v[208:211], v[86:89]
	v_mfma_f32_16x16x32_bf16 v[82:85], v[240:243], v[208:211], v[82:85]
	v_mfma_f32_16x16x32_bf16 v[78:81], v[232:235], v[216:219], v[78:81]
	v_mfma_f32_16x16x32_bf16 v[74:77], v[240:243], v[216:219], v[74:77]
	v_mfma_f32_16x16x32_bf16 v[70:73], v[232:235], v[224:227], v[70:73]
	v_mfma_f32_16x16x32_bf16 v[66:69], v[240:243], v[224:227], v[66:69]
	v_readfirstlane_b32 s39, v157
	v_lshl_add_u64 v[164:165], v[164:165], 0, s[28:29]
	s_mov_b32 m0, s39
	v_readfirstlane_b32 s39, v158
	s_barrier
	ds_read_b128 v[192:195], v169 offset:49152
	ds_read_b128 v[200:203], v169 offset:50176
	ds_read_b128 v[204:207], v170 offset:49152
	ds_read_b128 v[208:211], v170 offset:50176
	ds_read_b128 v[212:215], v171 offset:49152
	ds_read_b128 v[216:219], v171 offset:50176
	ds_read_b128 v[220:223], v172 offset:49152
	ds_read_b128 v[224:227], v172 offset:50176
	global_load_lds_dwordx4 v[164:165], off
	v_lshl_add_u64 v[164:165], v[196:197], 0, s[28:29]
	s_mov_b32 m0, s39
	s_nop 0
	global_load_lds_dwordx4 v[164:165], off
	s_barrier
	s_waitcnt lgkmcnt(0)
	s_waitcnt lgkmcnt(0)
	v_mfma_f32_16x16x32_bf16 v[62:65], v[176:179], v[192:195], v[62:65]
	v_mfma_f32_16x16x32_bf16 v[58:61], v[184:187], v[192:195], v[58:61]
	v_mfma_f32_16x16x32_bf16 v[54:57], v[176:179], v[204:207], v[54:57]
	v_mfma_f32_16x16x32_bf16 v[50:53], v[184:187], v[204:207], v[50:53]
	v_mfma_f32_16x16x32_bf16 v[46:49], v[176:179], v[212:215], v[46:49]
	v_mfma_f32_16x16x32_bf16 v[42:45], v[184:187], v[212:215], v[42:45]
	v_mfma_f32_16x16x32_bf16 v[38:41], v[176:179], v[220:223], v[38:41]
	v_mfma_f32_16x16x32_bf16 v[34:37], v[184:187], v[220:223], v[34:37]
	v_mfma_f32_16x16x32_bf16 v[62:65], v[180:183], v[200:203], v[62:65]
	v_mfma_f32_16x16x32_bf16 v[58:61], v[188:191], v[200:203], v[58:61]
	v_mfma_f32_16x16x32_bf16 v[54:57], v[180:183], v[208:211], v[54:57]
	v_mfma_f32_16x16x32_bf16 v[50:53], v[188:191], v[208:211], v[50:53]
	v_mfma_f32_16x16x32_bf16 v[46:49], v[180:183], v[216:219], v[46:49]
	v_mfma_f32_16x16x32_bf16 v[42:45], v[188:191], v[216:219], v[42:45]
	v_mfma_f32_16x16x32_bf16 v[38:41], v[180:183], v[224:227], v[38:41]
	v_mfma_f32_16x16x32_bf16 v[34:37], v[188:191], v[224:227], v[34:37]
	s_barrier
	v_readfirstlane_b32 s39, v159
	v_lshl_add_u64 v[164:165], v[244:245], 0, s[30:31]
	s_mov_b32 m0, s39
	v_readfirstlane_b32 s39, v160
	global_load_lds_dwordx4 v[164:165], off
	v_lshl_add_u64 v[164:165], v[246:247], 0, s[30:31]
	s_mov_b32 m0, s39
	s_nop 0
	global_load_lds_dwordx4 v[164:165], off
	s_waitcnt vmcnt(6)
	s_barrier
	v_mfma_f32_16x16x32_bf16 v[30:33], v[228:231], v[192:195], v[30:33]
	v_mfma_f32_16x16x32_bf16 v[26:29], v[236:239], v[192:195], v[26:29]
	v_mfma_f32_16x16x32_bf16 v[22:25], v[228:231], v[204:207], v[22:25]
	v_mfma_f32_16x16x32_bf16 v[18:21], v[236:239], v[204:207], v[18:21]
	v_mfma_f32_16x16x32_bf16 v[14:17], v[228:231], v[212:215], v[14:17]
	v_mfma_f32_16x16x32_bf16 v[10:13], v[236:239], v[212:215], v[10:13]
	v_mfma_f32_16x16x32_bf16 v[6:9], v[228:231], v[220:223], v[6:9]
	v_mfma_f32_16x16x32_bf16 v[2:5], v[236:239], v[220:223], v[2:5]
	v_mfma_f32_16x16x32_bf16 v[30:33], v[232:235], v[200:203], v[30:33]
	v_mfma_f32_16x16x32_bf16 v[26:29], v[240:243], v[200:203], v[26:29]
	v_mfma_f32_16x16x32_bf16 v[22:25], v[232:235], v[208:211], v[22:25]
	v_mfma_f32_16x16x32_bf16 v[18:21], v[240:243], v[208:211], v[18:21]
	v_mfma_f32_16x16x32_bf16 v[14:17], v[232:235], v[216:219], v[14:17]
	v_mfma_f32_16x16x32_bf16 v[10:13], v[240:243], v[216:219], v[10:13]
	v_mfma_f32_16x16x32_bf16 v[6:9], v[232:235], v[224:227], v[6:9]
	v_mfma_f32_16x16x32_bf16 v[2:5], v[240:243], v[224:227], v[2:5]
	s_add_i32 s38, s38, 2
	s_add_u32 s36, s36, 0x100
	s_addc_u32 s37, s37, 0
	s_cmp_lt_u32 s38, 40
	s_barrier
	s_cbranch_scc1 .LBB0_2580
	s_add_u32 s6, s6, 0x1580
	s_addc_u32 s7, s7, 0
	v_readfirstlane_b32 s36, v161
	v_lshl_add_u64 v[164:165], s[6:7], 0, v[132:133]
	s_mov_b32 m0, s36
	v_lshl_add_u64 v[160:161], s[6:7], 0, v[130:131]
	v_readfirstlane_b32 s6, v162
	ds_read_b128 v[140:143], v168
	ds_read_b128 v[144:147], v168 offset:1024
	ds_read_b128 v[148:151], v168 offset:2048
	ds_read_b128 v[152:155], v168 offset:3072
	ds_read_b128 v[156:159], v169
	ds_read_b128 v[176:179], v169 offset:1024
	ds_read_b128 v[180:183], v170
	ds_read_b128 v[184:187], v170 offset:1024
	ds_read_b128 v[188:191], v171
	ds_read_b128 v[192:195], v171 offset:1024
	ds_read_b128 v[200:203], v172
	ds_read_b128 v[204:207], v172 offset:1024
	global_load_lds_dwordx4 v[164:165], off
	s_mov_b32 m0, s6
	s_nop 0
	global_load_lds_dwordx4 v[160:161], off
	s_barrier
	s_waitcnt lgkmcnt(0)
	s_waitcnt lgkmcnt(0)
	v_mfma_f32_16x16x32_bf16 v[126:129], v[140:143], v[156:159], v[126:129]
	v_mfma_f32_16x16x32_bf16 v[122:125], v[148:151], v[156:159], v[122:125]
	v_mfma_f32_16x16x32_bf16 v[110:113], v[140:143], v[188:191], v[110:113]
	v_mfma_f32_16x16x32_bf16 v[106:109], v[148:151], v[188:191], v[106:109]
	v_mfma_f32_16x16x32_bf16 v[126:129], v[144:147], v[176:179], v[126:129]
	v_mfma_f32_16x16x32_bf16 v[122:125], v[152:155], v[176:179], v[122:125]
	v_mfma_f32_16x16x32_bf16 v[118:121], v[140:143], v[180:183], v[118:121]
	v_mfma_f32_16x16x32_bf16 v[114:117], v[148:151], v[180:183], v[114:117]
	v_mfma_f32_16x16x32_bf16 v[110:113], v[144:147], v[192:195], v[110:113]
	v_mfma_f32_16x16x32_bf16 v[106:109], v[152:155], v[192:195], v[106:109]
	v_mfma_f32_16x16x32_bf16 v[102:105], v[140:143], v[200:203], v[102:105]
	v_mfma_f32_16x16x32_bf16 v[98:101], v[148:151], v[200:203], v[98:101]
	v_mfma_f32_16x16x32_bf16 v[160:163], v[144:147], v[184:187], v[118:121]
	v_mfma_f32_16x16x32_bf16 v[208:211], v[152:155], v[184:187], v[114:117]
	v_mfma_f32_16x16x32_bf16 v[212:215], v[144:147], v[204:207], v[102:105]
	v_mfma_f32_16x16x32_bf16 v[216:219], v[152:155], v[204:207], v[98:101]
	s_barrier
	s_nop 1
	ds_read_b128 v[98:101], v173
	ds_read_b128 v[102:105], v173 offset:1024
	ds_read_b128 v[114:117], v173 offset:2048
	ds_read_b128 v[118:121], v173 offset:3072
	s_barrier
	s_waitcnt lgkmcnt(0)
	s_waitcnt lgkmcnt(0)
	v_mfma_f32_16x16x32_bf16 v[94:97], v[98:101], v[156:159], v[94:97]
	v_mfma_f32_16x16x32_bf16 v[90:93], v[114:117], v[156:159], v[90:93]
	v_mfma_f32_16x16x32_bf16 v[78:81], v[98:101], v[188:191], v[78:81]
	v_mfma_f32_16x16x32_bf16 v[74:77], v[114:117], v[188:191], v[74:77]
	v_mfma_f32_16x16x32_bf16 v[94:97], v[102:105], v[176:179], v[94:97]
	v_mfma_f32_16x16x32_bf16 v[90:93], v[118:121], v[176:179], v[90:93]
	v_mfma_f32_16x16x32_bf16 v[86:89], v[98:101], v[180:183], v[86:89]
	v_mfma_f32_16x16x32_bf16 v[82:85], v[114:117], v[180:183], v[82:85]
	v_mfma_f32_16x16x32_bf16 v[78:81], v[102:105], v[192:195], v[78:81]
	v_mfma_f32_16x16x32_bf16 v[74:77], v[118:121], v[192:195], v[74:77]
	v_mfma_f32_16x16x32_bf16 v[70:73], v[98:101], v[200:203], v[70:73]
	v_mfma_f32_16x16x32_bf16 v[66:69], v[114:117], v[200:203], v[66:69]
	v_mfma_f32_16x16x32_bf16 v[156:159], v[102:105], v[184:187], v[86:89]
	v_mfma_f32_16x16x32_bf16 v[176:179], v[118:121], v[184:187], v[82:85]
	v_mfma_f32_16x16x32_bf16 v[180:183], v[102:105], v[204:207], v[70:73]
	v_mfma_f32_16x16x32_bf16 v[184:187], v[118:121], v[204:207], v[66:69]
	s_barrier
	s_nop 1
	ds_read_b128 v[66:69], v169 offset:16384
	ds_read_b128 v[70:73], v169 offset:17408
	ds_read_b128 v[82:85], v170 offset:16384
	ds_read_b128 v[86:89], v170 offset:17408
	ds_read_b128 v[188:191], v171 offset:16384
	ds_read_b128 v[192:195], v171 offset:17408
	ds_read_b128 v[200:203], v172 offset:16384
	ds_read_b128 v[204:207], v172 offset:17408
	s_waitcnt vmcnt(4)
	s_barrier
	s_waitcnt lgkmcnt(0)
	s_waitcnt lgkmcnt(0)
	v_mfma_f32_16x16x32_bf16 v[62:65], v[140:143], v[66:69], v[62:65]
	v_mfma_f32_16x16x32_bf16 v[58:61], v[148:151], v[66:69], v[58:61]
	v_mfma_f32_16x16x32_bf16 v[46:49], v[140:143], v[188:191], v[46:49]
	v_mfma_f32_16x16x32_bf16 v[42:45], v[148:151], v[188:191], v[42:45]
	v_mfma_f32_16x16x32_bf16 v[62:65], v[144:147], v[70:73], v[62:65]
	v_mfma_f32_16x16x32_bf16 v[58:61], v[152:155], v[70:73], v[58:61]
	v_mfma_f32_16x16x32_bf16 v[54:57], v[140:143], v[82:85], v[54:57]
	v_mfma_f32_16x16x32_bf16 v[50:53], v[148:151], v[82:85], v[50:53]
	v_mfma_f32_16x16x32_bf16 v[46:49], v[144:147], v[192:195], v[46:49]
	v_mfma_f32_16x16x32_bf16 v[42:45], v[152:155], v[192:195], v[42:45]
	v_mfma_f32_16x16x32_bf16 v[38:41], v[140:143], v[200:203], v[38:41]
	v_mfma_f32_16x16x32_bf16 v[34:37], v[148:151], v[200:203], v[34:37]
	v_mfma_f32_16x16x32_bf16 v[220:223], v[144:147], v[86:89], v[54:57]
	v_mfma_f32_16x16x32_bf16 v[224:227], v[152:155], v[86:89], v[50:53]
	v_mfma_f32_16x16x32_bf16 v[140:143], v[144:147], v[204:207], v[38:41]
	v_mfma_f32_16x16x32_bf16 v[144:147], v[152:155], v[204:207], v[34:37]
	v_mfma_f32_16x16x32_bf16 v[30:33], v[98:101], v[66:69], v[30:33]
	v_mfma_f32_16x16x32_bf16 v[26:29], v[114:117], v[66:69], v[26:29]
	v_mfma_f32_16x16x32_bf16 v[14:17], v[98:101], v[188:191], v[14:17]
	v_mfma_f32_16x16x32_bf16 v[10:13], v[114:117], v[188:191], v[10:13]
	v_mfma_f32_16x16x32_bf16 v[30:33], v[102:105], v[70:73], v[30:33]
	v_mfma_f32_16x16x32_bf16 v[26:29], v[118:121], v[70:73], v[26:29]
	v_mfma_f32_16x16x32_bf16 v[22:25], v[98:101], v[82:85], v[22:25]
	v_mfma_f32_16x16x32_bf16 v[18:21], v[114:117], v[82:85], v[18:21]
	v_mfma_f32_16x16x32_bf16 v[14:17], v[102:105], v[192:195], v[14:17]
	v_mfma_f32_16x16x32_bf16 v[10:13], v[118:121], v[192:195], v[10:13]
	v_mfma_f32_16x16x32_bf16 v[6:9], v[98:101], v[200:203], v[6:9]
	v_mfma_f32_16x16x32_bf16 v[2:5], v[114:117], v[200:203], v[2:5]
	v_mfma_f32_16x16x32_bf16 v[148:151], v[102:105], v[86:89], v[22:25]
	v_mfma_f32_16x16x32_bf16 v[152:155], v[118:121], v[86:89], v[18:21]
	v_mfma_f32_16x16x32_bf16 v[188:191], v[102:105], v[204:207], v[6:9]
	v_mfma_f32_16x16x32_bf16 v[192:195], v[118:121], v[204:207], v[2:5]
	s_barrier
	s_nop 1
	ds_read_b128 v[2:5], v174
	ds_read_b128 v[6:9], v174 offset:1024
	ds_read_b128 v[200:203], v174 offset:2048
	ds_read_b128 v[204:207], v174 offset:3072
	ds_read_b128 v[18:21], v169 offset:32768
	ds_read_b128 v[22:25], v169 offset:33792
	ds_read_b128 v[34:37], v170 offset:32768
	ds_read_b128 v[38:41], v170 offset:33792
	ds_read_b128 v[50:53], v171 offset:32768
	ds_read_b128 v[54:57], v171 offset:33792
	ds_read_b128 v[228:231], v172 offset:32768
	ds_read_b128 v[232:235], v172 offset:33792
	s_waitcnt vmcnt(2)
	s_barrier
	s_waitcnt lgkmcnt(0)
	s_waitcnt lgkmcnt(0)
	v_mfma_f32_16x16x32_bf16 v[66:69], v[2:5], v[18:21], v[126:129]
	v_mfma_f32_16x16x32_bf16 v[114:117], v[6:9], v[22:25], v[66:69]
	v_mfma_f32_16x16x32_bf16 v[66:69], v[200:203], v[18:21], v[122:125]
	v_mfma_f32_16x16x32_bf16 v[118:121], v[204:207], v[22:25], v[66:69]
	v_mfma_f32_16x16x32_bf16 v[66:69], v[2:5], v[34:37], v[160:163]
	v_mfma_f32_16x16x32_bf16 v[98:101], v[6:9], v[38:41], v[66:69]
	v_mfma_f32_16x16x32_bf16 v[66:69], v[200:203], v[34:37], v[208:211]
	v_mfma_f32_16x16x32_bf16 v[102:105], v[204:207], v[38:41], v[66:69]
	v_mfma_f32_16x16x32_bf16 v[66:69], v[2:5], v[50:53], v[110:113]
	v_mfma_f32_16x16x32_bf16 v[82:85], v[6:9], v[54:57], v[66:69]
	v_mfma_f32_16x16x32_bf16 v[66:69], v[200:203], v[50:53], v[106:109]
	v_mfma_f32_16x16x32_bf16 v[86:89], v[204:207], v[54:57], v[66:69]
	v_mfma_f32_16x16x32_bf16 v[66:69], v[2:5], v[228:231], v[212:215]
	v_mfma_f32_16x16x32_bf16 v[70:73], v[200:203], v[228:231], v[216:219]
	v_mfma_f32_16x16x32_bf16 v[66:69], v[6:9], v[232:235], v[66:69]
	v_mfma_f32_16x16x32_bf16 v[70:73], v[204:207], v[232:235], v[70:73]
	s_barrier
	ds_read_b128 v[160:163], v175
	ds_read_b128 v[208:211], v175 offset:1024
	ds_read_b128 v[212:215], v175 offset:2048
	ds_read_b128 v[216:219], v175 offset:3072
	s_waitcnt vmcnt(0)
	s_barrier
	s_waitcnt lgkmcnt(0)
	s_waitcnt lgkmcnt(0)
	v_mfma_f32_16x16x32_bf16 v[94:97], v[160:163], v[18:21], v[94:97]
	v_mfma_f32_16x16x32_bf16 v[18:21], v[212:215], v[18:21], v[90:93]
	v_mfma_f32_16x16x32_bf16 v[122:125], v[216:219], v[22:25], v[18:21]
	v_mfma_f32_16x16x32_bf16 v[18:21], v[160:163], v[34:37], v[156:159]
	v_mfma_f32_16x16x32_bf16 v[110:113], v[208:211], v[38:41], v[18:21]
	v_mfma_f32_16x16x32_bf16 v[18:21], v[212:215], v[34:37], v[176:179]
	v_mfma_f32_16x16x32_bf16 v[106:109], v[216:219], v[38:41], v[18:21]
	v_mfma_f32_16x16x32_bf16 v[18:21], v[160:163], v[50:53], v[78:81]
	v_mfma_f32_16x16x32_bf16 v[126:129], v[208:211], v[22:25], v[94:97]
	v_mfma_f32_16x16x32_bf16 v[94:97], v[208:211], v[54:57], v[18:21]
	v_mfma_f32_16x16x32_bf16 v[18:21], v[212:215], v[50:53], v[74:77]
	v_mfma_f32_16x16x32_bf16 v[90:93], v[216:219], v[54:57], v[18:21]
	v_mfma_f32_16x16x32_bf16 v[18:21], v[160:163], v[228:231], v[180:183]
	v_mfma_f32_16x16x32_bf16 v[78:81], v[208:211], v[232:235], v[18:21]
	v_mfma_f32_16x16x32_bf16 v[18:21], v[212:215], v[228:231], v[184:187]
	v_mfma_f32_16x16x32_bf16 v[74:77], v[216:219], v[232:235], v[18:21]
	s_barrier
	ds_read_b128 v[156:159], v169 offset:49152
	ds_read_b128 v[176:179], v169 offset:50176
	ds_read_b128 v[180:183], v170 offset:49152
	ds_read_b128 v[184:187], v170 offset:50176
	ds_read_b128 v[228:231], v171 offset:49152
	ds_read_b128 v[232:235], v171 offset:50176
	ds_read_b128 v[236:239], v172 offset:49152
	ds_read_b128 v[240:243], v172 offset:50176
	s_barrier
	s_waitcnt lgkmcnt(0)
	s_waitcnt lgkmcnt(0)
	v_mfma_f32_16x16x32_bf16 v[18:21], v[2:5], v[156:159], v[62:65]
	v_mfma_f32_16x16x32_bf16 v[50:53], v[6:9], v[176:179], v[18:21]
	v_mfma_f32_16x16x32_bf16 v[18:21], v[200:203], v[156:159], v[58:61]
	v_mfma_f32_16x16x32_bf16 v[54:57], v[204:207], v[176:179], v[18:21]
	v_mfma_f32_16x16x32_bf16 v[18:21], v[2:5], v[180:183], v[220:223]
	v_mfma_f32_16x16x32_bf16 v[34:37], v[6:9], v[184:187], v[18:21]
	v_mfma_f32_16x16x32_bf16 v[18:21], v[200:203], v[180:183], v[224:227]
	v_mfma_f32_16x16x32_bf16 v[38:41], v[204:207], v[184:187], v[18:21]
	v_mfma_f32_16x16x32_bf16 v[18:21], v[2:5], v[228:231], v[46:49]
	v_mfma_f32_16x16x32_bf16 v[2:5], v[2:5], v[236:239], v[140:143]
	v_mfma_f32_16x16x32_bf16 v[18:21], v[6:9], v[232:235], v[18:21]
	v_mfma_f32_16x16x32_bf16 v[22:25], v[200:203], v[228:231], v[42:45]
	v_mfma_f32_16x16x32_bf16 v[2:5], v[6:9], v[240:243], v[2:5]
	v_mfma_f32_16x16x32_bf16 v[6:9], v[200:203], v[236:239], v[144:147]
	v_mfma_f32_16x16x32_bf16 v[22:25], v[204:207], v[232:235], v[22:25]
	v_mfma_f32_16x16x32_bf16 v[6:9], v[204:207], v[240:243], v[6:9]
	v_mfma_f32_16x16x32_bf16 v[26:29], v[212:215], v[156:159], v[26:29]
	v_mfma_f32_16x16x32_bf16 v[58:61], v[216:219], v[176:179], v[26:29]
	v_mfma_f32_16x16x32_bf16 v[26:29], v[160:163], v[180:183], v[148:151]
	v_mfma_f32_16x16x32_bf16 v[46:49], v[208:211], v[184:187], v[26:29]
	v_mfma_f32_16x16x32_bf16 v[26:29], v[212:215], v[180:183], v[152:155]
	v_mfma_f32_16x16x32_bf16 v[10:13], v[212:215], v[228:231], v[10:13]
	v_mfma_f32_16x16x32_bf16 v[30:33], v[160:163], v[156:159], v[30:33]
	v_mfma_f32_16x16x32_bf16 v[42:45], v[216:219], v[184:187], v[26:29]
	v_mfma_f32_16x16x32_bf16 v[14:17], v[160:163], v[228:231], v[14:17]
	v_mfma_f32_16x16x32_bf16 v[26:29], v[216:219], v[232:235], v[10:13]
	v_mfma_f32_16x16x32_bf16 v[10:13], v[160:163], v[236:239], v[188:191]
	v_mfma_f32_16x16x32_bf16 v[62:65], v[208:211], v[176:179], v[30:33]
	v_mfma_f32_16x16x32_bf16 v[30:33], v[208:211], v[232:235], v[14:17]
	v_mfma_f32_16x16x32_bf16 v[14:17], v[208:211], v[240:243], v[10:13]
	v_mfma_f32_16x16x32_bf16 v[10:13], v[212:215], v[236:239], v[192:195]
	v_mfma_f32_16x16x32_bf16 v[10:13], v[216:219], v[240:243], v[10:13]
	s_barrier
	s_and_saveexec_b64 s[6:7], s[2:3]
	s_cbranch_execz .LBB0_2583
	s_barrier
.LBB0_2583:
	s_setprio 0
	s_or_b64 exec, exec, s[6:7]
	v_mov_b32_e32 v134, v0
	s_lshl_b32 s6, s47, 8
	v_ashrrev_i32_e32 v140, 2, v134
	v_and_b32_e32 v140, 0xffffffc0, v140
	v_bfe_u32 v177, v134, 6, 2
	v_bfe_u32 v179, v134, 4, 2
	v_add_u32_e32 v140, s35, v140
	v_and_or_b32 v140, v134, 15, v140
	v_lshlrev_b32_e32 v134, 5, v177
	v_lshlrev_b32_e32 v141, 2, v179
	v_or3_b32 v142, v134, s6, v141
	v_ashrrev_i32_e32 v141, 31, v140
	v_lshlrev_b64 v[144:145], 11, v[140:141]
	v_lshl_add_u64 v[144:145], s[94:95], 0, v[144:145]
	v_ashrrev_i32_e32 v143, 31, v142
	v_lshl_add_u64 v[144:145], v[142:143], 1, v[144:145]
	global_load_dwordx2 v[146:147], v[144:145], off
	global_load_dwordx2 v[148:149], v[144:145], off offset:32
	global_load_dwordx2 v[150:151], v[144:145], off offset:256
	s_nop 0
	global_load_dwordx2 v[144:145], v[144:145], off offset:288
	v_and_b32_e32 v152, 64, v1
	v_add_u32_e32 v178, 64, v152
	v_xor_b32_e32 v134, 16, v1
	v_cmp_lt_i32_e32 vcc, v134, v178
	v_lshlrev_b32_e32 v177, 2, v177
	s_waitcnt vmcnt(0)
	v_lshlrev_b32_e32 v152, 16, v146
	v_and_b32_e32 v153, 0xffff0000, v146
	v_lshlrev_b32_e32 v146, 16, v147
	v_and_b32_e32 v147, 0xffff0000, v147
	v_lshlrev_b32_e32 v154, 16, v148
	v_and_b32_e32 v155, 0xffff0000, v148
	v_lshlrev_b32_e32 v156, 16, v149
	v_and_b32_e32 v157, 0xffff0000, v149
	v_lshlrev_b32_e32 v158, 16, v150
	v_and_b32_e32 v159, 0xffff0000, v150
	v_lshlrev_b32_e32 v160, 16, v151
	v_and_b32_e32 v161, 0xffff0000, v151
	v_lshlrev_b32_e32 v162, 16, v144
	v_and_b32_e32 v163, 0xffff0000, v144
	v_pk_add_f32 v[148:149], v[116:117], v[146:147]
	v_pk_add_f32 v[150:151], v[114:115], v[152:153]
	v_pk_add_f32 v[146:147], v[118:119], v[154:155]
	v_lshlrev_b32_e32 v164, 16, v145
	v_and_b32_e32 v165, 0xffff0000, v145
	v_pk_add_f32 v[144:145], v[120:121], v[156:157]
	v_pk_add_f32 v[120:121], v[126:127], v[158:159]
	v_pk_add_f32 v[116:117], v[122:123], v[162:163]
	v_mul_f32_e32 v122, v151, v151
	v_mul_f32_e32 v123, v147, v147
	v_pk_add_f32 v[114:115], v[124:125], v[164:165]
	v_mul_f32_e32 v124, v121, v121
	v_fmac_f32_e32 v122, v150, v150
	v_fmac_f32_e32 v123, v146, v146
	v_pk_add_f32 v[118:119], v[128:129], v[160:161]
	v_mul_f32_e32 v125, v117, v117
	v_fmac_f32_e32 v124, v120, v120
	v_fmac_f32_e32 v122, v148, v148
	v_fmac_f32_e32 v123, v144, v144
	v_fmac_f32_e32 v125, v116, v116
	v_fmac_f32_e32 v124, v118, v118
	v_fmac_f32_e32 v122, v149, v149
	v_fmac_f32_e32 v123, v145, v145
	v_fmac_f32_e32 v125, v114, v114
	v_fmac_f32_e32 v124, v119, v119
	v_add_f32_e32 v122, v122, v123
	v_cndmask_b32_e32 v134, v1, v134, vcc
	v_add_f32_e32 v122, v122, v124
	v_fmac_f32_e32 v125, v115, v115
	v_lshlrev_b32_e32 v176, 2, v134
	v_add_f32_e32 v122, v122, v125
	ds_bpermute_b32 v123, v176, v122
	v_xor_b32_e32 v124, 32, v1
	v_cmp_lt_i32_e32 vcc, v124, v178
	v_subrev_u32_e32 v134, s35, v140
	s_waitcnt lgkmcnt(0)
	v_add_f32_e32 v122, v122, v123
	v_cndmask_b32_e32 v124, v1, v124, vcc
	v_lshlrev_b32_e32 v178, 2, v124
	ds_bpermute_b32 v123, v178, v122
	v_cmp_eq_u32_e32 vcc, 0, v179
	s_and_saveexec_b64 s[6:7], vcc
	s_cbranch_execz .LBB0_2585
	s_waitcnt lgkmcnt(0)
	v_add_f32_e32 v122, v122, v123
	v_lshlrev_b32_e32 v123, 4, v134
	v_add3_u32 v123, 16, v123, v177
	ds_write_b32 v123, v122
